# GEMM K-loops: scalar bookkeeping moved out of MFMA-segment tails into the following load segments (behind the ds_reads)
# baseline (speedup 1.0000x reference)
; #define PG8_STAGE(bufoff, gbase, voff) do { _Pragma("unroll") for (int _i = 0; _i < 2; ++_i) \
;         __builtin_amdgcn_global_load_lds((const unsigned*)((const char*)(gbase) + (voff)[_i]), (LAS unsigned*)(lds + (bufoff) + ldsw + _i * 8192), 16, 0, 0); } while (0)
; #define PG8_LDA(dst, b, h) do { _Pragma("unroll") for (int m = 0; m < 4; ++m) _Pragma("unroll") for (int k = 0; k < 2; ++k) dst[m][k] = *(const LAS bf16x8*)(lds + PG8_SA(b, h) + aoff + m * 2048 + k * 1024); } while (0)
; #define PG8_LDB(dst, b, h) do { _Pragma("unroll") for (int n = 0; n < 2; ++n) _Pragma("unroll") for (int k = 0; k < 2; ++k) dst[n][k] = *(const LAS bf16x8*)(lds + PG8_SB(b, h) + boff + n * 2048 + k * 1024); } while (0)
; #define PG8_MMA(ai, bj, At, Bt) do { __builtin_amdgcn_s_setprio(1); _Pragma("unroll") for (int m = 0; m < 4; ++m) _Pragma("unroll") for (int n = 0; n < 2; ++n) _Pragma("unroll") for (int k = 0; k < 2; ++k) \
;         acc[ai][bj][m][n] = __builtin_amdgcn_mfma_f32_16x16x32_bf16(Bt[n][k], At[m][k], acc[ai][bj][m][n], 0, 0, 0); __builtin_amdgcn_s_setprio(0); } while (0)
; #define PG8_WAIT_V(n) asm volatile("s_waitcnt vmcnt(" #n ")" ::: "memory")
; #define PG8_WAIT_L(n) asm volatile("s_waitcnt lgkmcnt(" #n ")" ::: "memory")
; template <class Epi>
; __device__ __forceinline__ void gemm_phase(LAS unsigned char* lds, const Gemm g, const StaticOrder& S, const Epi& E) {
;     ...
;         for (int t = 0; t < nt; t += 2) {
;             const bool last = (t == nt - 2);
;             const char* a1 = cA + (size_t)(t + 1) * kstep;
;             const char* a2 = last ? nA : cA + (size_t)(t + 2) * kstep; const char* b2 = last ? nB : cB + (size_t)(t + 2) * kstep;
;             const char* a3 = a2 + kstep; const char* b3 = b2 + kstep;
;             PG8_LDB(B0, 0, 0); PG8_SCHED; PG8_LDA(At, 0, 0); PG8_STAGE(PG8_SA(1, 1), a1 + hstep, voffA);
;             PG8_WAIT_L(8); PG8_BAR; PG8_WAIT_L(0); PG8_MMA(0, 0, At, B0); PG8_BAR; PG8_SCHED;
;             PG8_LDB(B1, 0, 1); PG8_STAGE(PG8_SB(0, 0), b2, voffB);
;             PG8_BAR; PG8_WAIT_L(0); PG8_MMA(0, 1, At, B1); PG8_BAR;
;             PG8_LDA(At, 0, 1); PG8_STAGE(PG8_SA(0, 0), a2, voffA);
;             PG8_BAR; PG8_WAIT_L(0); PG8_MMA(1, 0, At, B0); PG8_BAR; PG8_SCHED;
;             PG8_STAGE(PG8_SB(0, 1), b2 + hstep, voffB);
;             PG8_WAIT_V(6); PG8_BAR; PG8_MMA(1, 1, At, B1); PG8_BAR;
.LBB0_64:
	s_add_u32 s58, s56, 0xfff80080
	s_addc_u32 s59, s57, -1
	s_add_i32 s86, 0, 0x10000
	s_cmp_eq_u32 s85, 28
	s_cselect_b32 s61, s49, s59
	s_cselect_b32 s60, s81, s58
	s_cselect_b32 s59, s47, s84
	s_cselect_b32 s58, s82, s83
	s_add_i32 m0, s55, 0xc000
	ds_read_b128 v[170:173], v151
	ds_read_b128 v[174:177], v151 offset:1024
	ds_read_b128 v[178:181], v151 offset:2048
	ds_read_b128 v[182:185], v151 offset:3072
	ds_read_b128 v[186:189], v151 offset:4096
	ds_read_b128 v[190:193], v151 offset:5120
	ds_read_b128 v[194:197], v151 offset:6144
	ds_read_b128 v[198:201], v151 offset:7168
	global_load_lds_dwordx4 v136, s[56:57]
	s_add_i32 m0, s55, 0xe000
	s_nop 0
	global_load_lds_dwordx4 v138, s[56:57]
	s_waitcnt lgkmcnt(8)
	s_barrier
	s_waitcnt lgkmcnt(0)
	v_mfma_f32_16x16x32_bf16 v[126:129], v[154:157], v[170:173], v[126:129]
	v_mfma_f32_16x16x32_bf16 v[122:125], v[162:165], v[170:173], v[122:125]
	v_mfma_f32_16x16x32_bf16 v[110:113], v[154:157], v[178:181], v[110:113]
	v_mfma_f32_16x16x32_bf16 v[106:109], v[162:165], v[178:181], v[106:109]
	v_mfma_f32_16x16x32_bf16 v[94:97], v[154:157], v[186:189], v[94:97]
	v_mfma_f32_16x16x32_bf16 v[90:93], v[162:165], v[186:189], v[90:93]
	v_mfma_f32_16x16x32_bf16 v[78:81], v[154:157], v[194:197], v[78:81]
	v_mfma_f32_16x16x32_bf16 v[74:77], v[162:165], v[194:197], v[74:77]
	v_mfma_f32_16x16x32_bf16 v[126:129], v[158:161], v[174:177], v[126:129]
	v_mfma_f32_16x16x32_bf16 v[122:125], v[166:169], v[174:177], v[122:125]
	v_mfma_f32_16x16x32_bf16 v[110:113], v[158:161], v[182:185], v[110:113]
	v_mfma_f32_16x16x32_bf16 v[106:109], v[166:169], v[182:185], v[106:109]
	v_mfma_f32_16x16x32_bf16 v[94:97], v[158:161], v[190:193], v[94:97]
	v_mfma_f32_16x16x32_bf16 v[90:93], v[166:169], v[190:193], v[90:93]
	v_mfma_f32_16x16x32_bf16 v[78:81], v[158:161], v[198:201], v[78:81]
	v_mfma_f32_16x16x32_bf16 v[74:77], v[166:169], v[198:201], v[74:77]
	s_barrier
	s_add_i32 s88, 0, 0x14000
	s_add_i32 s86, s86, s69
	s_add_u32 s98, s58, s22
	s_addc_u32 s99, s59, s23
	s_mov_b32 m0, s86
	ds_read_b128 v[208:211], v202 offset:16384
	ds_read_b128 v[212:215], v202 offset:17408
	ds_read_b128 v[216:219], v202 offset:18432
	ds_read_b128 v[220:223], v202 offset:19456
	global_load_lds_dwordx4 v0, s[58:59]
	s_add_i32 m0, s86, 0x2000
	s_nop 0
	global_load_lds_dwordx4 v130, s[58:59]
	s_barrier
	s_waitcnt lgkmcnt(0)
	v_mfma_f32_16x16x32_bf16 v[118:121], v[208:211], v[170:173], v[118:121]
	v_mfma_f32_16x16x32_bf16 v[114:117], v[216:219], v[170:173], v[114:117]
	v_mfma_f32_16x16x32_bf16 v[102:105], v[208:211], v[178:181], v[102:105]
	v_mfma_f32_16x16x32_bf16 v[98:101], v[216:219], v[178:181], v[98:101]
	v_mfma_f32_16x16x32_bf16 v[86:89], v[208:211], v[186:189], v[86:89]
	v_mfma_f32_16x16x32_bf16 v[82:85], v[216:219], v[186:189], v[82:85]
	v_mfma_f32_16x16x32_bf16 v[70:73], v[208:211], v[194:197], v[70:73]
	v_mfma_f32_16x16x32_bf16 v[66:69], v[216:219], v[194:197], v[66:69]
	v_mfma_f32_16x16x32_bf16 v[118:121], v[212:215], v[174:177], v[118:121]
	v_mfma_f32_16x16x32_bf16 v[114:117], v[220:223], v[174:177], v[114:117]
	v_mfma_f32_16x16x32_bf16 v[102:105], v[212:215], v[182:185], v[102:105]
	v_mfma_f32_16x16x32_bf16 v[98:101], v[220:223], v[182:185], v[98:101]
	v_mfma_f32_16x16x32_bf16 v[86:89], v[212:215], v[190:193], v[86:89]
	v_mfma_f32_16x16x32_bf16 v[82:85], v[220:223], v[190:193], v[82:85]
	v_mfma_f32_16x16x32_bf16 v[70:73], v[212:215], v[198:201], v[70:73]
	v_mfma_f32_16x16x32_bf16 v[66:69], v[220:223], v[198:201], v[66:69]
	s_barrier
	ds_read_b128 v[170:173], v151 offset:16384
	ds_read_b128 v[174:177], v151 offset:17408
	ds_read_b128 v[178:181], v151 offset:18432
	ds_read_b128 v[182:185], v151 offset:19456
	ds_read_b128 v[186:189], v151 offset:20480
	ds_read_b128 v[190:193], v151 offset:21504
	ds_read_b128 v[194:197], v151 offset:22528
	s_mov_b32 m0, s55
	s_add_u32 s100, s60, s22
	s_addc_u32 s101, s61, s23
	ds_read_b128 v[198:201], v151 offset:23552
	global_load_lds_dwordx4 v134, s[60:61]
	s_mov_b32 m0, s72
	s_nop 0
	global_load_lds_dwordx4 v132, s[60:61]
	s_waitcnt vmcnt(10)
	s_barrier
	s_waitcnt lgkmcnt(0)
	v_mfma_f32_16x16x32_bf16 v[62:65], v[154:157], v[170:173], v[62:65]
	v_mfma_f32_16x16x32_bf16 v[58:61], v[162:165], v[170:173], v[58:61]
	v_mfma_f32_16x16x32_bf16 v[54:57], v[154:157], v[178:181], v[54:57]
	v_mfma_f32_16x16x32_bf16 v[46:49], v[162:165], v[178:181], v[46:49]
	v_mfma_f32_16x16x32_bf16 v[38:41], v[154:157], v[186:189], v[38:41]
	v_mfma_f32_16x16x32_bf16 v[30:33], v[162:165], v[186:189], v[30:33]
	v_mfma_f32_16x16x32_bf16 v[22:25], v[154:157], v[194:197], v[22:25]
	v_mfma_f32_16x16x32_bf16 v[14:17], v[162:165], v[194:197], v[14:17]
	v_mfma_f32_16x16x32_bf16 v[62:65], v[158:161], v[174:177], v[62:65]
	v_mfma_f32_16x16x32_bf16 v[58:61], v[166:169], v[174:177], v[58:61]
	v_mfma_f32_16x16x32_bf16 v[54:57], v[158:161], v[182:185], v[54:57]
	v_mfma_f32_16x16x32_bf16 v[46:49], v[166:169], v[182:185], v[46:49]
	v_mfma_f32_16x16x32_bf16 v[38:41], v[158:161], v[190:193], v[38:41]
	v_mfma_f32_16x16x32_bf16 v[30:33], v[166:169], v[190:193], v[30:33]
	v_mfma_f32_16x16x32_bf16 v[22:25], v[158:161], v[198:201], v[22:25]
	v_mfma_f32_16x16x32_bf16 v[14:17], v[166:169], v[198:201], v[14:17]
	s_barrier
	ds_read_b128 v[154:157], v202 offset:32768
	ds_read_b128 v[158:161], v202 offset:33792
	ds_read_b128 v[162:165], v202 offset:34816
	ds_read_b128 v[166:169], v202 offset:35840
	s_add_u32 s86, s58, 0x80000
	s_addc_u32 s87, s59, 0
	s_add_i32 s88, s88, s69
	s_mov_b32 m0, s88
	s_nop 0
	global_load_lds_dwordx4 v0, s[86:87]
	s_add_i32 m0, s88, 0x2000
	s_nop 0
	global_load_lds_dwordx4 v130, s[86:87]
	s_waitcnt vmcnt(6)
	s_barrier
; #define PG8_STAGE(bufoff, gbase, voff) do { _Pragma("unroll") for (int _i = 0; _i < 2; ++_i) \
;         __builtin_amdgcn_global_load_lds((const unsigned*)((const char*)(gbase) + (voff)[_i]), (LAS unsigned*)(lds + (bufoff) + ldsw + _i * 8192), 16, 0, 0); } while (0)
; #define PG8_LDA(dst, b, h) do { _Pragma("unroll") for (int m = 0; m < 4; ++m) _Pragma("unroll") for (int k = 0; k < 2; ++k) dst[m][k] = *(const LAS bf16x8*)(lds + PG8_SA(b, h) + aoff + m * 2048 + k * 1024); } while (0)
; #define PG8_LDB(dst, b, h) do { _Pragma("unroll") for (int n = 0; n < 2; ++n) _Pragma("unroll") for (int k = 0; k < 2; ++k) dst[n][k] = *(const LAS bf16x8*)(lds + PG8_SB(b, h) + boff + n * 2048 + k * 1024); } while (0)
; #define PG8_MMA(ai, bj, At, Bt) do { __builtin_amdgcn_s_setprio(1); _Pragma("unroll") for (int m = 0; m < 4; ++m) _Pragma("unroll") for (int n = 0; n < 2; ++n) _Pragma("unroll") for (int k = 0; k < 2; ++k) \
;         acc[ai][bj][m][n] = __builtin_amdgcn_mfma_f32_16x16x32_bf16(Bt[n][k], At[m][k], acc[ai][bj][m][n], 0, 0, 0); __builtin_amdgcn_s_setprio(0); } while (0)
; #define PG8_WAIT_V(n) asm volatile("s_waitcnt vmcnt(" #n ")" ::: "memory")
; #define PG8_WAIT_L(n) asm volatile("s_waitcnt lgkmcnt(" #n ")" ::: "memory")
; #define PG8_BAR __builtin_amdgcn_s_barrier()
; #define PG8_SCHED __builtin_amdgcn_sched_barrier(0)
; template <class Epi>
; __device__ __forceinline__ void gemm_phase(LAS unsigned char* lds, const Gemm g, const StaticOrder& S, const Epi& E) {
;     ...
;             PG8_WAIT_V(6); PG8_BAR; PG8_MMA(1, 1, At, B1); PG8_BAR;
;             PG8_LDB(B0, 1, 0); PG8_SCHED; PG8_LDA(At, 1, 0); PG8_STAGE(PG8_SA(0, 1), a2 + hstep, voffA);
;             PG8_WAIT_L(8); PG8_BAR; PG8_WAIT_L(0); PG8_MMA(0, 0, At, B0); PG8_BAR; PG8_SCHED;
;             PG8_LDB(B1, 1, 1); PG8_STAGE(PG8_SB(1, 0), b3, voffB);
;             PG8_BAR; PG8_WAIT_L(0); PG8_MMA(0, 1, At, B1); PG8_BAR;
;             PG8_LDA(At, 1, 1); PG8_STAGE(PG8_SA(1, 0), a3, voffA);
;             PG8_BAR; PG8_WAIT_L(0); PG8_MMA(1, 0, At, B0); PG8_BAR; PG8_SCHED;
	v_mfma_f32_16x16x32_bf16 v[50:53], v[208:211], v[170:173], v[50:53]
	v_mfma_f32_16x16x32_bf16 v[42:45], v[216:219], v[170:173], v[42:45]
	v_mfma_f32_16x16x32_bf16 v[34:37], v[208:211], v[178:181], v[34:37]
	v_mfma_f32_16x16x32_bf16 v[26:29], v[216:219], v[178:181], v[26:29]
	v_mfma_f32_16x16x32_bf16 v[18:21], v[208:211], v[186:189], v[18:21]
	v_mfma_f32_16x16x32_bf16 v[10:13], v[216:219], v[186:189], v[10:13]
	v_mfma_f32_16x16x32_bf16 v[6:9], v[208:211], v[194:197], v[6:9]
	v_mfma_f32_16x16x32_bf16 v[2:5], v[216:219], v[194:197], v[2:5]
	v_mfma_f32_16x16x32_bf16 v[50:53], v[212:215], v[174:177], v[50:53]
	v_mfma_f32_16x16x32_bf16 v[42:45], v[220:223], v[174:177], v[42:45]
	v_mfma_f32_16x16x32_bf16 v[34:37], v[212:215], v[182:185], v[34:37]
	v_mfma_f32_16x16x32_bf16 v[26:29], v[220:223], v[182:185], v[26:29]
	v_mfma_f32_16x16x32_bf16 v[18:21], v[212:215], v[190:193], v[18:21]
	v_mfma_f32_16x16x32_bf16 v[10:13], v[220:223], v[190:193], v[10:13]
	v_mfma_f32_16x16x32_bf16 v[6:9], v[212:215], v[198:201], v[6:9]
	v_mfma_f32_16x16x32_bf16 v[2:5], v[220:223], v[198:201], v[2:5]
	s_barrier
	s_add_u32 s60, s60, 0x80000
	s_addc_u32 s61, s61, 0
	s_mov_b32 m0, s73
	ds_read_b128 v[170:173], v151 offset:32768
	ds_read_b128 v[174:177], v151 offset:33792
	ds_read_b128 v[178:181], v151 offset:34816
	ds_read_b128 v[182:185], v151 offset:35840
	ds_read_b128 v[186:189], v151 offset:36864
	ds_read_b128 v[190:193], v151 offset:37888
	ds_read_b128 v[194:197], v151 offset:38912
	s_add_i32 s86, 0, 0x18000
	ds_read_b128 v[198:201], v151 offset:39936
	global_load_lds_dwordx4 v134, s[60:61]
	s_mov_b32 m0, s74
	s_nop 0
	global_load_lds_dwordx4 v132, s[60:61]
	s_waitcnt lgkmcnt(8)
	s_barrier
	s_waitcnt lgkmcnt(0)
	v_mfma_f32_16x16x32_bf16 v[126:129], v[154:157], v[170:173], v[126:129]
	v_mfma_f32_16x16x32_bf16 v[122:125], v[162:165], v[170:173], v[122:125]
	v_mfma_f32_16x16x32_bf16 v[110:113], v[154:157], v[178:181], v[110:113]
	v_mfma_f32_16x16x32_bf16 v[106:109], v[162:165], v[178:181], v[106:109]
	v_mfma_f32_16x16x32_bf16 v[94:97], v[154:157], v[186:189], v[94:97]
	v_mfma_f32_16x16x32_bf16 v[90:93], v[162:165], v[186:189], v[90:93]
	v_mfma_f32_16x16x32_bf16 v[78:81], v[154:157], v[194:197], v[78:81]
	v_mfma_f32_16x16x32_bf16 v[74:77], v[162:165], v[194:197], v[74:77]
	v_mfma_f32_16x16x32_bf16 v[126:129], v[158:161], v[174:177], v[126:129]
	v_mfma_f32_16x16x32_bf16 v[122:125], v[166:169], v[174:177], v[122:125]
	v_mfma_f32_16x16x32_bf16 v[110:113], v[158:161], v[182:185], v[110:113]
	v_mfma_f32_16x16x32_bf16 v[106:109], v[166:169], v[182:185], v[106:109]
	v_mfma_f32_16x16x32_bf16 v[94:97], v[158:161], v[190:193], v[94:97]
	v_mfma_f32_16x16x32_bf16 v[90:93], v[166:169], v[190:193], v[90:93]
	v_mfma_f32_16x16x32_bf16 v[78:81], v[158:161], v[198:201], v[78:81]
	v_mfma_f32_16x16x32_bf16 v[74:77], v[166:169], v[198:201], v[74:77]
	s_barrier
	s_add_i32 s60, 0, 0x1c000
	s_add_i32 s61, s86, s69
	s_mov_b32 m0, s61
	ds_read_b128 v[208:211], v202 offset:49152
	ds_read_b128 v[212:215], v202 offset:50176
	ds_read_b128 v[216:219], v202 offset:51200
	ds_read_b128 v[220:223], v202 offset:52224
	global_load_lds_dwordx4 v0, s[98:99]
	s_add_i32 m0, s61, 0x2000
	s_nop 0
	global_load_lds_dwordx4 v130, s[98:99]
	s_barrier
	s_waitcnt lgkmcnt(0)
	v_mfma_f32_16x16x32_bf16 v[118:121], v[208:211], v[170:173], v[118:121]
	v_mfma_f32_16x16x32_bf16 v[114:117], v[216:219], v[170:173], v[114:117]
	v_mfma_f32_16x16x32_bf16 v[102:105], v[208:211], v[178:181], v[102:105]
	v_mfma_f32_16x16x32_bf16 v[98:101], v[216:219], v[178:181], v[98:101]
	v_mfma_f32_16x16x32_bf16 v[86:89], v[208:211], v[186:189], v[86:89]
	v_mfma_f32_16x16x32_bf16 v[82:85], v[216:219], v[186:189], v[82:85]
	v_mfma_f32_16x16x32_bf16 v[70:73], v[208:211], v[194:197], v[70:73]
	v_mfma_f32_16x16x32_bf16 v[66:69], v[216:219], v[194:197], v[66:69]
	v_mfma_f32_16x16x32_bf16 v[118:121], v[212:215], v[174:177], v[118:121]
	v_mfma_f32_16x16x32_bf16 v[114:117], v[220:223], v[174:177], v[114:117]
	v_mfma_f32_16x16x32_bf16 v[102:105], v[212:215], v[182:185], v[102:105]
	v_mfma_f32_16x16x32_bf16 v[98:101], v[220:223], v[182:185], v[98:101]
	v_mfma_f32_16x16x32_bf16 v[86:89], v[212:215], v[190:193], v[86:89]
	v_mfma_f32_16x16x32_bf16 v[82:85], v[220:223], v[190:193], v[82:85]
	v_mfma_f32_16x16x32_bf16 v[70:73], v[212:215], v[198:201], v[70:73]
	v_mfma_f32_16x16x32_bf16 v[66:69], v[220:223], v[198:201], v[66:69]
	s_barrier
	ds_read_b128 v[170:173], v151 offset:49152
	ds_read_b128 v[174:177], v151 offset:50176
	ds_read_b128 v[178:181], v151 offset:51200
	ds_read_b128 v[182:185], v151 offset:52224
	ds_read_b128 v[186:189], v151 offset:53248
	ds_read_b128 v[190:193], v151 offset:54272
	ds_read_b128 v[194:197], v151 offset:55296
	s_mov_b32 m0, s76
	ds_read_b128 v[198:201], v151 offset:56320
	global_load_lds_dwordx4 v134, s[100:101]
	s_mov_b32 m0, s77
	s_nop 0
	global_load_lds_dwordx4 v132, s[100:101]
	s_waitcnt vmcnt(10)
	s_barrier
	s_waitcnt lgkmcnt(0)
	v_mfma_f32_16x16x32_bf16 v[62:65], v[154:157], v[170:173], v[62:65]
	v_mfma_f32_16x16x32_bf16 v[58:61], v[162:165], v[170:173], v[58:61]
	v_mfma_f32_16x16x32_bf16 v[54:57], v[154:157], v[178:181], v[54:57]
	v_mfma_f32_16x16x32_bf16 v[46:49], v[162:165], v[178:181], v[46:49]
	v_mfma_f32_16x16x32_bf16 v[38:41], v[154:157], v[186:189], v[38:41]
	v_mfma_f32_16x16x32_bf16 v[30:33], v[162:165], v[186:189], v[30:33]
	v_mfma_f32_16x16x32_bf16 v[22:25], v[154:157], v[194:197], v[22:25]
	v_mfma_f32_16x16x32_bf16 v[14:17], v[162:165], v[194:197], v[14:17]
	v_mfma_f32_16x16x32_bf16 v[62:65], v[158:161], v[174:177], v[62:65]
	v_mfma_f32_16x16x32_bf16 v[58:61], v[166:169], v[174:177], v[58:61]
	v_mfma_f32_16x16x32_bf16 v[54:57], v[158:161], v[182:185], v[54:57]
	v_mfma_f32_16x16x32_bf16 v[46:49], v[166:169], v[182:185], v[46:49]
	v_mfma_f32_16x16x32_bf16 v[38:41], v[158:161], v[190:193], v[38:41]
	v_mfma_f32_16x16x32_bf16 v[30:33], v[166:169], v[190:193], v[30:33]
	v_mfma_f32_16x16x32_bf16 v[22:25], v[158:161], v[198:201], v[22:25]
	v_mfma_f32_16x16x32_bf16 v[14:17], v[166:169], v[198:201], v[14:17]
	s_barrier
; __device__ __forceinline__ unsigned pk2(float lo, float hi) { f32x2 v = {lo, hi}; bf16x2_t b = __builtin_convertvector(v, bf16x2_t); return __builtin_bit_cast(unsigned, b); }
; #define PG8_STAGE(bufoff, gbase, voff) do { _Pragma("unroll") for (int _i = 0; _i < 2; ++_i) \
;         __builtin_amdgcn_global_load_lds((const unsigned*)((const char*)(gbase) + (voff)[_i]), (LAS unsigned*)(lds + (bufoff) + ldsw + _i * 8192), 16, 0, 0); } while (0)
; #define PG8_WAIT_V(n) asm volatile("s_waitcnt vmcnt(" #n ")" ::: "memory")
; #define PG8_WAIT_L(n) asm volatile("s_waitcnt lgkmcnt(" #n ")" ::: "memory")
; #define PG8_BAR __builtin_amdgcn_s_barrier()
;     __device__ __forceinline__ void operator()(const AccT& acc, const Unit& u, int wr, int wc, int fr, int fq) const {
;         const int row0 = u.pm * BM + wr * 64 + fr, col0 = u.pn * BM + wc * 32 + 8 * fq;
;         float rsv[8];
;         if (ss) {
;             const int ln = (fq << 4) | fr;
;             float sa = ss[u.pm * BM + wr * 64 + ln], sb = ss[u.pm * BM + HALF + wr * 64 + ln];
;             sa = __builtin_amdgcn_rsqf(sa * (1.0f / DM) + EPS); sb = __builtin_amdgcn_rsqf(sb * (1.0f / DM) + EPS);
; #pragma unroll
;             for (int m = 0; m < 4; ++m) { rsv[m] = __shfl(sa, 16 * m + fr); rsv[4 + m] = __shfl(sb, 16 * m + fr); }
;         } else {
; #pragma unroll
;             for (int i = 0; i < 8; ++i) rsv[i] = 1.0f;
;         }
; #pragma unroll
;         for (int ai = 0; ai < 2; ++ai)
; #pragma unroll
;             for (int m = 0; m < 4; ++m) {
;                 const int row = row0 + ai * HALF + m * 16;
;                 const float rs = rsv[ai * 4 + m];
; #pragma unroll
;                 for (int bj = 0; bj < 2; ++bj) {
;                     const f32x4 v0 = acc[ai][bj][m][0] * rs, v1 = acc[ai][bj][m][1] * rs;
;                     u32x4 w; w.x = pk2(v0[0], v0[1]); w.y = pk2(v0[2], v0[3]); w.z = pk2(v1[0], v1[1]); w.w = pk2(v1[2], v1[3]);
;                     *(u32x4*)(out + (size_t)row * ldo + col0 + bj * HALF) = w;
; template <class Epi>
; __device__ __forceinline__ void gemm_phase(LAS unsigned char* lds, const Gemm g, const StaticOrder& S, const Epi& E) {
;     ...
;             PG8_BAR; PG8_WAIT_L(0); PG8_MMA(1, 0, At, B0); PG8_BAR; PG8_SCHED;
;             PG8_STAGE(PG8_SB(1, 1), b3 + hstep, voffB);
;             PG8_WAIT_V(6); PG8_BAR; PG8_MMA(1, 1, At, B1); PG8_BAR;
	ds_read_b128 v[154:157], v202
	ds_read_b128 v[158:161], v202 offset:1024
	ds_read_b128 v[162:165], v202 offset:2048
	s_add_i32 s85, s85, 2
	s_add_u32 s56, s56, 0x100
	s_addc_u32 s57, s57, 0
	s_add_u32 s83, s83, 0x100
	s_addc_u32 s84, s84, 0
	ds_read_b128 v[166:169], v202 offset:3072
	s_add_u32 s58, s58, 0x80080
	s_addc_u32 s59, s59, 0
	s_add_i32 s60, s60, s69
	s_mov_b32 m0, s60
	s_nop 0
	global_load_lds_dwordx4 v0, s[58:59]
	s_add_i32 m0, s60, 0x2000
	s_nop 0
	global_load_lds_dwordx4 v130, s[58:59]
	s_waitcnt vmcnt(6)
	s_barrier
	v_mfma_f32_16x16x32_bf16 v[50:53], v[208:211], v[170:173], v[50:53]
	v_mfma_f32_16x16x32_bf16 v[42:45], v[216:219], v[170:173], v[42:45]
	v_mfma_f32_16x16x32_bf16 v[34:37], v[208:211], v[178:181], v[34:37]
	v_mfma_f32_16x16x32_bf16 v[26:29], v[216:219], v[178:181], v[26:29]
	v_mfma_f32_16x16x32_bf16 v[18:21], v[208:211], v[186:189], v[18:21]
	v_mfma_f32_16x16x32_bf16 v[10:13], v[216:219], v[186:189], v[10:13]
	v_mfma_f32_16x16x32_bf16 v[6:9], v[208:211], v[194:197], v[6:9]
	v_mfma_f32_16x16x32_bf16 v[2:5], v[216:219], v[194:197], v[2:5]
	v_mfma_f32_16x16x32_bf16 v[50:53], v[212:215], v[174:177], v[50:53]
	v_mfma_f32_16x16x32_bf16 v[42:45], v[220:223], v[174:177], v[42:45]
	v_mfma_f32_16x16x32_bf16 v[34:37], v[212:215], v[182:185], v[34:37]
	v_mfma_f32_16x16x32_bf16 v[26:29], v[220:223], v[182:185], v[26:29]
	v_mfma_f32_16x16x32_bf16 v[18:21], v[212:215], v[190:193], v[18:21]
	v_mfma_f32_16x16x32_bf16 v[10:13], v[220:223], v[190:193], v[10:13]
	v_mfma_f32_16x16x32_bf16 v[6:9], v[212:215], v[198:201], v[6:9]
	v_mfma_f32_16x16x32_bf16 v[2:5], v[220:223], v[198:201], v[2:5]
	s_cmp_gt_u32 s85, 29
	s_barrier
	s_cbranch_scc0 .LBB0_64
	s_waitcnt lgkmcnt(0)
	s_lshl_b32 s47, s54, 8
	s_add_i32 s47, s47, s75
	v_or_b32_e32 v154, s47, v145
	v_ashrrev_i32_e32 v155, 31, v154
	v_lshl_add_u64 v[154:155], v[154:155], 2, s[2:3]
	global_load_dword v140, v[154:155], off
	v_add_u32_e32 v154, s47, v147
	v_ashrrev_i32_e32 v155, 31, v154
	v_lshl_add_u64 v[154:155], v[154:155], 2, s[2:3]
	global_load_dword v142, v[154:155], off
	v_lshl_or_b32 v158, s80, 8, v149
	v_ashrrev_i32_e32 v159, 31, v158
	s_and_b64 vcc, exec, s[36:37]
	s_mov_b32 s80, s46
	s_mov_b32 s54, s48
	s_mov_b64 s[58:59], s[52:53]
	s_waitcnt vmcnt(0)
	v_fmamk_f32 v140, v140, 0x3a000000, v233
	v_rsq_f32_e32 v140, v140
	v_fmamk_f32 v142, v142, 0x3a000000, v233
	ds_bpermute_b32 v154, v152, v140
	v_rsq_f32_e32 v153, v142
	ds_bpermute_b32 v156, v152, v140 offset:64
	ds_bpermute_b32 v150, v152, v140 offset:128
	ds_bpermute_b32 v148, v152, v140 offset:192
	ds_bpermute_b32 v146, v152, v153
	ds_bpermute_b32 v144, v152, v153 offset:64
	ds_bpermute_b32 v142, v152, v153 offset:128
	ds_bpermute_b32 v140, v152, v153 offset:192
	v_or_b32_e32 v153, s47, v141
	s_waitcnt lgkmcnt(0)
	v_pk_mul_f32 v[126:127], v[126:127], v[154:155] op_sel_hi:[1,0]
	v_pk_mul_f32 v[122:123], v[122:123], v[154:155] op_sel_hi:[1,0]
	v_pk_mul_f32 v[128:129], v[128:129], v[154:155] op_sel_hi:[1,0]
	v_pk_mul_f32 v[160:161], v[124:125], v[154:155] op_sel_hi:[1,0]
	v_cvt_pk_bf16_f32 v124, v126, v127
	v_cvt_pk_bf16_f32 v126, v122, v123
	v_mad_i64_i32 v[122:123], s[56:57], v153, s63, 0
	v_cvt_pk_bf16_f32 v125, v128, v129
	v_lshl_add_u64 v[128:129], v[122:123], 1, s[44:45]
	v_lshlrev_b64 v[122:123], 1, v[158:159]
	v_cvt_pk_bf16_f32 v127, v160, v161
	v_lshl_add_u64 v[128:129], v[128:129], 0, v[122:123]
	global_store_dwordx4 v[128:129], v[124:127], off
	v_pk_mul_f32 v[120:121], v[120:121], v[154:155] op_sel_hi:[1,0]
	v_pk_mul_f32 v[118:119], v[118:119], v[154:155] op_sel_hi:[1,0]
	v_pk_mul_f32 v[124:125], v[116:117], v[154:155] op_sel_hi:[1,0]
	v_pk_mul_f32 v[116:117], v[114:115], v[154:155] op_sel_hi:[1,0]
	v_cvt_pk_bf16_f32 v114, v118, v119
	v_cvt_pk_bf16_f32 v115, v120, v121
	v_cvt_pk_bf16_f32 v116, v116, v117
	v_cvt_pk_bf16_f32 v117, v124, v125
	global_store_dwordx4 v[128:129], v[114:117], off offset:256
	v_pk_mul_f32 v[110:111], v[110:111], v[156:157] op_sel_hi:[1,0]
	v_pk_mul_f32 v[112:113], v[112:113], v[156:157] op_sel_hi:[1,0]
	v_or_b32_e32 v116, 16, v153
	v_pk_mul_f32 v[114:115], v[108:109], v[156:157] op_sel_hi:[1,0]
	v_pk_mul_f32 v[108:109], v[106:107], v[156:157] op_sel_hi:[1,0]
	v_cvt_pk_bf16_f32 v106, v110, v111
	v_mad_i64_i32 v[110:111], s[56:57], v116, s63, 0
	v_lshl_add_u64 v[110:111], v[110:111], 1, s[44:45]
	v_cvt_pk_bf16_f32 v107, v112, v113
	v_cvt_pk_bf16_f32 v108, v108, v109
	v_cvt_pk_bf16_f32 v109, v114, v115
	v_lshl_add_u64 v[110:111], v[110:111], 0, v[122:123]
	global_store_dwordx4 v[110:111], v[106:109], off
	v_pk_mul_f32 v[104:105], v[104:105], v[156:157] op_sel_hi:[1,0]
	v_pk_mul_f32 v[102:103], v[102:103], v[156:157] op_sel_hi:[1,0]
	v_pk_mul_f32 v[106:107], v[100:101], v[156:157] op_sel_hi:[1,0]
	v_pk_mul_f32 v[100:101], v[98:99], v[156:157] op_sel_hi:[1,0]
	v_cvt_pk_bf16_f32 v98, v102, v103
	v_cvt_pk_bf16_f32 v99, v104, v105
	v_cvt_pk_bf16_f32 v100, v100, v101
	v_cvt_pk_bf16_f32 v101, v106, v107
	global_store_dwordx4 v[110:111], v[98:101], off offset:256
	v_pk_mul_f32 v[94:95], v[94:95], v[150:151] op_sel_hi:[1,0]
	v_pk_mul_f32 v[96:97], v[96:97], v[150:151] op_sel_hi:[1,0]
	v_or_b32_e32 v100, 32, v153
	v_pk_mul_f32 v[98:99], v[92:93], v[150:151] op_sel_hi:[1,0]
	v_pk_mul_f32 v[92:93], v[90:91], v[150:151] op_sel_hi:[1,0]
	v_cvt_pk_bf16_f32 v90, v94, v95
	v_mad_i64_i32 v[94:95], s[56:57], v100, s63, 0
	v_lshl_add_u64 v[94:95], v[94:95], 1, s[44:45]
	v_cvt_pk_bf16_f32 v91, v96, v97
	v_cvt_pk_bf16_f32 v92, v92, v93
	v_cvt_pk_bf16_f32 v93, v98, v99
	v_lshl_add_u64 v[94:95], v[94:95], 0, v[122:123]
	global_store_dwordx4 v[94:95], v[90:93], off
	v_pk_mul_f32 v[88:89], v[88:89], v[150:151] op_sel_hi:[1,0]
; __device__ __forceinline__ unsigned pk2(float lo, float hi) { f32x2 v = {lo, hi}; bf16x2_t b = __builtin_convertvector(v, bf16x2_t); return __builtin_bit_cast(unsigned, b); }
; #define PG8_WAIT_V(n) asm volatile("s_waitcnt vmcnt(" #n ")" ::: "memory")
; #define PG8_BAR __builtin_amdgcn_s_barrier()
;     __device__ __forceinline__ void operator()(const AccT& acc, const Unit& u, int wr, int wc, int fr, int fq) const {
;     ...
; #pragma unroll
;         for (int ai = 0; ai < 2; ++ai)
; #pragma unroll
;             for (int m = 0; m < 4; ++m) {
;                 const int row = row0 + ai * HALF + m * 16;
;                 const float rs = rsv[ai * 4 + m];
; #pragma unroll
;                 for (int bj = 0; bj < 2; ++bj) {
;                     const f32x4 v0 = acc[ai][bj][m][0] * rs, v1 = acc[ai][bj][m][1] * rs;
;                     u32x4 w; w.x = pk2(v0[0], v0[1]); w.y = pk2(v0[2], v0[3]); w.z = pk2(v1[0], v1[1]); w.w = pk2(v1[2], v1[3]);
;                     *(u32x4*)(out + (size_t)row * ldo + col0 + bj * HALF) = w;
;                 }
; template <class Epi>
; __device__ __forceinline__ void gemm_phase(LAS unsigned char* lds, const Gemm g, const StaticOrder& S, const Epi& E) {
;     ...
;         E(acc, cur, wr, wc, fr, fq);
;         if (!has_next) break;
; #pragma unroll
;         for (int a = 0; a < 2; ++a)
; #pragma unroll
;             for (int b = 0; b < 2; ++b)
; #pragma unroll
;                 for (int m = 0; m < 4; ++m)
; #pragma unroll
;                     for (int n = 0; n < 2; ++n) acc[a][b][m][n] = (f32x4){0.f, 0.f, 0.f, 0.f};
;         cur = nxt; cA = nA; cB = nB; ++ui;
;     }
;     PG8_WAIT_V(0);
;     if (wr == 0) PG8_BAR;
	v_pk_mul_f32 v[86:87], v[86:87], v[150:151] op_sel_hi:[1,0]
	v_pk_mul_f32 v[90:91], v[84:85], v[150:151] op_sel_hi:[1,0]
	v_pk_mul_f32 v[84:85], v[82:83], v[150:151] op_sel_hi:[1,0]
	v_cvt_pk_bf16_f32 v82, v86, v87
	v_cvt_pk_bf16_f32 v83, v88, v89
	v_cvt_pk_bf16_f32 v84, v84, v85
	v_cvt_pk_bf16_f32 v85, v90, v91
	global_store_dwordx4 v[94:95], v[82:85], off offset:256
	v_pk_mul_f32 v[78:79], v[78:79], v[148:149] op_sel_hi:[1,0]
	v_pk_mul_f32 v[80:81], v[80:81], v[148:149] op_sel_hi:[1,0]
	v_or_b32_e32 v84, 48, v153
	v_pk_mul_f32 v[82:83], v[76:77], v[148:149] op_sel_hi:[1,0]
	v_pk_mul_f32 v[76:77], v[74:75], v[148:149] op_sel_hi:[1,0]
	v_cvt_pk_bf16_f32 v74, v78, v79
	v_mad_i64_i32 v[78:79], s[56:57], v84, s63, 0
	v_lshl_add_u64 v[78:79], v[78:79], 1, s[44:45]
	v_cvt_pk_bf16_f32 v75, v80, v81
	v_cvt_pk_bf16_f32 v76, v76, v77
	v_cvt_pk_bf16_f32 v77, v82, v83
	v_lshl_add_u64 v[78:79], v[78:79], 0, v[122:123]
	global_store_dwordx4 v[78:79], v[74:77], off
	v_pk_mul_f32 v[72:73], v[72:73], v[148:149] op_sel_hi:[1,0]
	v_pk_mul_f32 v[70:71], v[70:71], v[148:149] op_sel_hi:[1,0]
	v_pk_mul_f32 v[74:75], v[68:69], v[148:149] op_sel_hi:[1,0]
	v_pk_mul_f32 v[68:69], v[66:67], v[148:149] op_sel_hi:[1,0]
	v_cvt_pk_bf16_f32 v66, v70, v71
	v_cvt_pk_bf16_f32 v67, v72, v73
	v_cvt_pk_bf16_f32 v68, v68, v69
	v_cvt_pk_bf16_f32 v69, v74, v75
	global_store_dwordx4 v[78:79], v[66:69], off offset:256
	v_pk_mul_f32 v[62:63], v[62:63], v[146:147] op_sel_hi:[1,0]
	v_pk_mul_f32 v[64:65], v[64:65], v[146:147] op_sel_hi:[1,0]
	v_add_u32_e32 v68, 0x80, v153
	v_pk_mul_f32 v[66:67], v[60:61], v[146:147] op_sel_hi:[1,0]
	v_pk_mul_f32 v[60:61], v[58:59], v[146:147] op_sel_hi:[1,0]
	v_cvt_pk_bf16_f32 v58, v62, v63
	v_mad_i64_i32 v[62:63], s[56:57], v68, s63, 0
	v_lshl_add_u64 v[62:63], v[62:63], 1, s[44:45]
	v_cvt_pk_bf16_f32 v59, v64, v65
	v_cvt_pk_bf16_f32 v60, v60, v61
	v_cvt_pk_bf16_f32 v61, v66, v67
	v_lshl_add_u64 v[62:63], v[62:63], 0, v[122:123]
	global_store_dwordx4 v[62:63], v[58:61], off
	v_pk_mul_f32 v[52:53], v[52:53], v[146:147] op_sel_hi:[1,0]
	v_pk_mul_f32 v[50:51], v[50:51], v[146:147] op_sel_hi:[1,0]
	v_pk_mul_f32 v[58:59], v[44:45], v[146:147] op_sel_hi:[1,0]
	v_pk_mul_f32 v[44:45], v[42:43], v[146:147] op_sel_hi:[1,0]
	v_cvt_pk_bf16_f32 v42, v50, v51
	v_cvt_pk_bf16_f32 v43, v52, v53
	v_cvt_pk_bf16_f32 v44, v44, v45
	v_cvt_pk_bf16_f32 v45, v58, v59
	global_store_dwordx4 v[62:63], v[42:45], off offset:256
	v_add_u32_e32 v50, 0x90, v153
	v_pk_mul_f32 v[46:47], v[46:47], v[144:145] op_sel_hi:[1,0]
	v_pk_mul_f32 v[44:45], v[56:57], v[144:145] op_sel_hi:[1,0]
	v_pk_mul_f32 v[42:43], v[54:55], v[144:145] op_sel_hi:[1,0]
	v_pk_mul_f32 v[48:49], v[48:49], v[144:145] op_sel_hi:[1,0]
	v_cvt_pk_bf16_f32 v42, v42, v43
	v_cvt_pk_bf16_f32 v43, v44, v45
	v_cvt_pk_bf16_f32 v44, v46, v47
	v_mad_i64_i32 v[46:47], s[56:57], v50, s63, 0
	v_lshl_add_u64 v[46:47], v[46:47], 1, s[44:45]
	v_cvt_pk_bf16_f32 v45, v48, v49
	v_lshl_add_u64 v[46:47], v[46:47], 0, v[122:123]
	global_store_dwordx4 v[46:47], v[42:45], off
	v_pk_mul_f32 v[36:37], v[36:37], v[144:145] op_sel_hi:[1,0]
	v_pk_mul_f32 v[34:35], v[34:35], v[144:145] op_sel_hi:[1,0]
	v_pk_mul_f32 v[42:43], v[28:29], v[144:145] op_sel_hi:[1,0]
	v_pk_mul_f32 v[28:29], v[26:27], v[144:145] op_sel_hi:[1,0]
	v_cvt_pk_bf16_f32 v26, v34, v35
	v_cvt_pk_bf16_f32 v27, v36, v37
	v_cvt_pk_bf16_f32 v28, v28, v29
	v_cvt_pk_bf16_f32 v29, v42, v43
	global_store_dwordx4 v[46:47], v[26:29], off offset:256
	v_add_u32_e32 v34, 0xa0, v153
	v_pk_mul_f32 v[30:31], v[30:31], v[142:143] op_sel_hi:[1,0]
	v_pk_mul_f32 v[28:29], v[40:41], v[142:143] op_sel_hi:[1,0]
	v_pk_mul_f32 v[26:27], v[38:39], v[142:143] op_sel_hi:[1,0]
	v_pk_mul_f32 v[32:33], v[32:33], v[142:143] op_sel_hi:[1,0]
	v_cvt_pk_bf16_f32 v26, v26, v27
	v_cvt_pk_bf16_f32 v27, v28, v29
	v_cvt_pk_bf16_f32 v28, v30, v31
	v_mad_i64_i32 v[30:31], s[56:57], v34, s63, 0
	v_lshl_add_u64 v[30:31], v[30:31], 1, s[44:45]
	v_cvt_pk_bf16_f32 v29, v32, v33
	v_lshl_add_u64 v[30:31], v[30:31], 0, v[122:123]
	global_store_dwordx4 v[30:31], v[26:29], off
	v_pk_mul_f32 v[20:21], v[20:21], v[142:143] op_sel_hi:[1,0]
	v_pk_mul_f32 v[18:19], v[18:19], v[142:143] op_sel_hi:[1,0]
	v_pk_mul_f32 v[26:27], v[12:13], v[142:143] op_sel_hi:[1,0]
	v_pk_mul_f32 v[12:13], v[10:11], v[142:143] op_sel_hi:[1,0]
	v_cvt_pk_bf16_f32 v10, v18, v19
	v_cvt_pk_bf16_f32 v11, v20, v21
	v_cvt_pk_bf16_f32 v12, v12, v13
	v_cvt_pk_bf16_f32 v13, v26, v27
	global_store_dwordx4 v[30:31], v[10:13], off offset:256
	v_add_u32_e32 v18, 0xb0, v153
	v_pk_mul_f32 v[14:15], v[14:15], v[140:141] op_sel_hi:[1,0]
	v_pk_mul_f32 v[12:13], v[24:25], v[140:141] op_sel_hi:[1,0]
	v_pk_mul_f32 v[10:11], v[22:23], v[140:141] op_sel_hi:[1,0]
	v_pk_mul_f32 v[16:17], v[16:17], v[140:141] op_sel_hi:[1,0]
	v_cvt_pk_bf16_f32 v10, v10, v11
	v_cvt_pk_bf16_f32 v11, v12, v13
	v_cvt_pk_bf16_f32 v12, v14, v15
	v_mad_i64_i32 v[14:15], s[56:57], v18, s63, 0
	v_lshl_add_u64 v[14:15], v[14:15], 1, s[44:45]
	v_cvt_pk_bf16_f32 v13, v16, v17
	v_lshl_add_u64 v[14:15], v[14:15], 0, v[122:123]
	global_store_dwordx4 v[14:15], v[10:13], off
	v_pk_mul_f32 v[8:9], v[8:9], v[140:141] op_sel_hi:[1,0]
	v_pk_mul_f32 v[6:7], v[6:7], v[140:141] op_sel_hi:[1,0]
	v_pk_mul_f32 v[10:11], v[4:5], v[140:141] op_sel_hi:[1,0]
	v_pk_mul_f32 v[4:5], v[2:3], v[140:141] op_sel_hi:[1,0]
	v_cvt_pk_bf16_f32 v2, v6, v7
	v_cvt_pk_bf16_f32 v3, v8, v9
	v_cvt_pk_bf16_f32 v4, v4, v5
	v_cvt_pk_bf16_f32 v5, v10, v11
	s_mov_b64 s[56:57], s[50:51]
	global_store_dwordx4 v[14:15], v[2:5], off offset:256
	s_cbranch_vccz .LBB0_61
	s_waitcnt vmcnt(0)
	s_cmpk_gt_u32 s64, 0xff
	s_cbranch_scc1 .LBB0_68
	s_barrier

; #define PG8_STAGE(bufoff, gbase, voff) do { _Pragma("unroll") for (int _i = 0; _i < 2; ++_i) \
;         __builtin_amdgcn_global_load_lds((const unsigned*)((const char*)(gbase) + (voff)[_i]), (LAS unsigned*)(lds + (bufoff) + ldsw + _i * 8192), 16, 0, 0); } while (0)
; #define PG8_LDA(dst, b, h) do { _Pragma("unroll") for (int m = 0; m < 4; ++m) _Pragma("unroll") for (int k = 0; k < 2; ++k) dst[m][k] = *(const LAS bf16x8*)(lds + PG8_SA(b, h) + aoff + m * 2048 + k * 1024); } while (0)
; #define PG8_LDB(dst, b, h) do { _Pragma("unroll") for (int n = 0; n < 2; ++n) _Pragma("unroll") for (int k = 0; k < 2; ++k) dst[n][k] = *(const LAS bf16x8*)(lds + PG8_SB(b, h) + boff + n * 2048 + k * 1024); } while (0)
; #define PG8_MMA(ai, bj, At, Bt) do { __builtin_amdgcn_s_setprio(1); _Pragma("unroll") for (int m = 0; m < 4; ++m) _Pragma("unroll") for (int n = 0; n < 2; ++n) _Pragma("unroll") for (int k = 0; k < 2; ++k) \
;         acc[ai][bj][m][n] = __builtin_amdgcn_mfma_f32_16x16x32_bf16(Bt[n][k], At[m][k], acc[ai][bj][m][n], 0, 0, 0); __builtin_amdgcn_s_setprio(0); } while (0)
; #define PG8_WAIT_V(n) asm volatile("s_waitcnt vmcnt(" #n ")" ::: "memory")
; #define PG8_WAIT_L(n) asm volatile("s_waitcnt lgkmcnt(" #n ")" ::: "memory")
; template <class Epi>
; __device__ __forceinline__ void gemm_phase(LAS unsigned char* lds, const Gemm g, const StaticOrder& S, const Epi& E) {
;     ...
;         for (int t = 0; t < nt; t += 2) {
;             const bool last = (t == nt - 2);
;             const char* a1 = cA + (size_t)(t + 1) * kstep;
;             const char* a2 = last ? nA : cA + (size_t)(t + 2) * kstep; const char* b2 = last ? nB : cB + (size_t)(t + 2) * kstep;
;             const char* a3 = a2 + kstep; const char* b3 = b2 + kstep;
;             PG8_LDB(B0, 0, 0); PG8_SCHED; PG8_LDA(At, 0, 0); PG8_STAGE(PG8_SA(1, 1), a1 + hstep, voffA);
;             PG8_WAIT_L(8); PG8_BAR; PG8_WAIT_L(0); PG8_MMA(0, 0, At, B0); PG8_BAR; PG8_SCHED;
;             PG8_LDB(B1, 0, 1); PG8_STAGE(PG8_SB(0, 0), b2, voffB);
;             PG8_BAR; PG8_WAIT_L(0); PG8_MMA(0, 1, At, B1); PG8_BAR;
;             PG8_LDA(At, 0, 1); PG8_STAGE(PG8_SA(0, 0), a2, voffA);
;             PG8_BAR; PG8_WAIT_L(0); PG8_MMA(1, 0, At, B0); PG8_BAR; PG8_SCHED;
;             PG8_STAGE(PG8_SB(0, 1), b2 + hstep, voffB);
;             PG8_WAIT_V(6); PG8_BAR; PG8_MMA(1, 1, At, B1); PG8_BAR;
.LBB0_77:
	s_add_u32 s56, s54, 0xfff80080
	s_addc_u32 s57, s55, -1
	s_add_i32 s81, 0, 0x10000
	s_cmp_eq_u32 s80, 28
	s_cselect_b32 s59, s49, s57
	s_cselect_b32 s58, s76, s56
	s_cselect_b32 s57, s47, s79
	s_cselect_b32 s56, s77, s78
	s_add_i32 m0, s65, 0xc000
	ds_read_b128 v[160:163], v143
	ds_read_b128 v[164:167], v143 offset:1024
	ds_read_b128 v[168:171], v143 offset:2048
	ds_read_b128 v[172:175], v143 offset:3072
	ds_read_b128 v[176:179], v143 offset:4096
	ds_read_b128 v[180:183], v143 offset:5120
	ds_read_b128 v[184:187], v143 offset:6144
	ds_read_b128 v[188:191], v143 offset:7168
	global_load_lds_dwordx4 v136, s[54:55]
	s_add_i32 m0, s65, 0xe000
	s_nop 0
	global_load_lds_dwordx4 v138, s[54:55]
	s_waitcnt lgkmcnt(8)
	s_barrier
	s_waitcnt lgkmcnt(0)
	v_mfma_f32_16x16x32_bf16 v[126:129], v[144:147], v[160:163], v[126:129]
	v_mfma_f32_16x16x32_bf16 v[122:125], v[152:155], v[160:163], v[122:125]
	v_mfma_f32_16x16x32_bf16 v[118:121], v[144:147], v[168:171], v[118:121]
	v_mfma_f32_16x16x32_bf16 v[114:117], v[152:155], v[168:171], v[114:117]
	v_mfma_f32_16x16x32_bf16 v[102:105], v[144:147], v[176:179], v[102:105]
	v_mfma_f32_16x16x32_bf16 v[98:101], v[152:155], v[176:179], v[98:101]
	v_mfma_f32_16x16x32_bf16 v[86:89], v[144:147], v[184:187], v[86:89]
	v_mfma_f32_16x16x32_bf16 v[82:85], v[152:155], v[184:187], v[82:85]
	v_mfma_f32_16x16x32_bf16 v[126:129], v[148:151], v[164:167], v[126:129]
	v_mfma_f32_16x16x32_bf16 v[122:125], v[156:159], v[164:167], v[122:125]
	v_mfma_f32_16x16x32_bf16 v[118:121], v[148:151], v[172:175], v[118:121]
	v_mfma_f32_16x16x32_bf16 v[114:117], v[156:159], v[172:175], v[114:117]
	v_mfma_f32_16x16x32_bf16 v[102:105], v[148:151], v[180:183], v[102:105]
	v_mfma_f32_16x16x32_bf16 v[98:101], v[156:159], v[180:183], v[98:101]
	v_mfma_f32_16x16x32_bf16 v[86:89], v[148:151], v[188:191], v[86:89]
	v_mfma_f32_16x16x32_bf16 v[82:85], v[156:159], v[188:191], v[82:85]
	s_barrier
	s_add_i32 s84, 0, 0x14000
	s_add_i32 s81, s81, s64
	ds_read_b128 v[192:195], v202 offset:16384
	ds_read_b128 v[196:199], v202 offset:17408
	ds_read_b128 v[208:211], v202 offset:18432
	ds_read_b128 v[212:215], v202 offset:19456
	s_mov_b32 m0, s81
	s_add_u32 s98, s56, s22
	s_addc_u32 s99, s57, s23
	global_load_lds_dwordx4 v0, s[56:57]
	s_add_i32 m0, s81, 0x2000
	s_nop 0
	global_load_lds_dwordx4 v130, s[56:57]
	s_barrier
	s_waitcnt lgkmcnt(0)
	v_mfma_f32_16x16x32_bf16 v[110:113], v[192:195], v[160:163], v[110:113]
	v_mfma_f32_16x16x32_bf16 v[106:109], v[208:211], v[160:163], v[106:109]
	v_mfma_f32_16x16x32_bf16 v[94:97], v[192:195], v[168:171], v[94:97]
	v_mfma_f32_16x16x32_bf16 v[90:93], v[208:211], v[168:171], v[90:93]
	v_mfma_f32_16x16x32_bf16 v[78:81], v[192:195], v[176:179], v[78:81]
	v_mfma_f32_16x16x32_bf16 v[74:77], v[208:211], v[176:179], v[74:77]
	v_mfma_f32_16x16x32_bf16 v[70:73], v[192:195], v[184:187], v[70:73]
	v_mfma_f32_16x16x32_bf16 v[66:69], v[208:211], v[184:187], v[66:69]
	v_mfma_f32_16x16x32_bf16 v[110:113], v[196:199], v[164:167], v[110:113]
	v_mfma_f32_16x16x32_bf16 v[106:109], v[212:215], v[164:167], v[106:109]
	v_mfma_f32_16x16x32_bf16 v[94:97], v[196:199], v[172:175], v[94:97]
	v_mfma_f32_16x16x32_bf16 v[90:93], v[212:215], v[172:175], v[90:93]
	v_mfma_f32_16x16x32_bf16 v[78:81], v[196:199], v[180:183], v[78:81]
	v_mfma_f32_16x16x32_bf16 v[74:77], v[212:215], v[180:183], v[74:77]
	v_mfma_f32_16x16x32_bf16 v[70:73], v[196:199], v[188:191], v[70:73]
	v_mfma_f32_16x16x32_bf16 v[66:69], v[212:215], v[188:191], v[66:69]
	s_barrier
	ds_read_b128 v[160:163], v143 offset:16384
	ds_read_b128 v[164:167], v143 offset:17408
	ds_read_b128 v[168:171], v143 offset:18432
	ds_read_b128 v[172:175], v143 offset:19456
	ds_read_b128 v[176:179], v143 offset:20480
	ds_read_b128 v[180:183], v143 offset:21504
	ds_read_b128 v[184:187], v143 offset:22528
	s_mov_b32 m0, s65
	s_add_u32 s100, s58, s22
	s_addc_u32 s101, s59, s23
	ds_read_b128 v[188:191], v143 offset:23552
	global_load_lds_dwordx4 v134, s[58:59]
	s_mov_b32 m0, s68
	s_nop 0
	global_load_lds_dwordx4 v132, s[58:59]
	s_waitcnt vmcnt(10)
	s_barrier
	s_waitcnt lgkmcnt(0)
	v_mfma_f32_16x16x32_bf16 v[62:65], v[144:147], v[160:163], v[62:65]
	v_mfma_f32_16x16x32_bf16 v[58:61], v[152:155], v[160:163], v[58:61]
	v_mfma_f32_16x16x32_bf16 v[54:57], v[144:147], v[168:171], v[54:57]
	v_mfma_f32_16x16x32_bf16 v[50:53], v[152:155], v[168:171], v[50:53]
	v_mfma_f32_16x16x32_bf16 v[38:41], v[144:147], v[176:179], v[38:41]
	v_mfma_f32_16x16x32_bf16 v[34:37], v[152:155], v[176:179], v[34:37]
	v_mfma_f32_16x16x32_bf16 v[22:25], v[144:147], v[184:187], v[22:25]
	v_mfma_f32_16x16x32_bf16 v[18:21], v[152:155], v[184:187], v[18:21]
	v_mfma_f32_16x16x32_bf16 v[62:65], v[148:151], v[164:167], v[62:65]
	v_mfma_f32_16x16x32_bf16 v[58:61], v[156:159], v[164:167], v[58:61]
	v_mfma_f32_16x16x32_bf16 v[54:57], v[148:151], v[172:175], v[54:57]
	v_mfma_f32_16x16x32_bf16 v[50:53], v[156:159], v[172:175], v[50:53]
	v_mfma_f32_16x16x32_bf16 v[38:41], v[148:151], v[180:183], v[38:41]
	v_mfma_f32_16x16x32_bf16 v[34:37], v[156:159], v[180:183], v[34:37]
	v_mfma_f32_16x16x32_bf16 v[22:25], v[148:151], v[188:191], v[22:25]
	v_mfma_f32_16x16x32_bf16 v[18:21], v[156:159], v[188:191], v[18:21]
	s_barrier
	ds_read_b128 v[144:147], v202 offset:32768
	ds_read_b128 v[148:151], v202 offset:33792
	ds_read_b128 v[152:155], v202 offset:34816
	ds_read_b128 v[156:159], v202 offset:35840
	s_add_u32 s82, s56, 0x80000
	s_addc_u32 s83, s57, 0
	s_add_i32 s81, s84, s64
	s_mov_b32 m0, s81
	s_nop 0
	global_load_lds_dwordx4 v0, s[82:83]
	s_add_i32 m0, s81, 0x2000
	s_nop 0
	global_load_lds_dwordx4 v130, s[82:83]
	s_waitcnt vmcnt(6)
	s_barrier
; #define PG8_STAGE(bufoff, gbase, voff) do { _Pragma("unroll") for (int _i = 0; _i < 2; ++_i) \
;         __builtin_amdgcn_global_load_lds((const unsigned*)((const char*)(gbase) + (voff)[_i]), (LAS unsigned*)(lds + (bufoff) + ldsw + _i * 8192), 16, 0, 0); } while (0)
; #define PG8_LDA(dst, b, h) do { _Pragma("unroll") for (int m = 0; m < 4; ++m) _Pragma("unroll") for (int k = 0; k < 2; ++k) dst[m][k] = *(const LAS bf16x8*)(lds + PG8_SA(b, h) + aoff + m * 2048 + k * 1024); } while (0)
; #define PG8_LDB(dst, b, h) do { _Pragma("unroll") for (int n = 0; n < 2; ++n) _Pragma("unroll") for (int k = 0; k < 2; ++k) dst[n][k] = *(const LAS bf16x8*)(lds + PG8_SB(b, h) + boff + n * 2048 + k * 1024); } while (0)
; #define PG8_MMA(ai, bj, At, Bt) do { __builtin_amdgcn_s_setprio(1); _Pragma("unroll") for (int m = 0; m < 4; ++m) _Pragma("unroll") for (int n = 0; n < 2; ++n) _Pragma("unroll") for (int k = 0; k < 2; ++k) \
;         acc[ai][bj][m][n] = __builtin_amdgcn_mfma_f32_16x16x32_bf16(Bt[n][k], At[m][k], acc[ai][bj][m][n], 0, 0, 0); __builtin_amdgcn_s_setprio(0); } while (0)
; #define PG8_WAIT_V(n) asm volatile("s_waitcnt vmcnt(" #n ")" ::: "memory")
; #define PG8_WAIT_L(n) asm volatile("s_waitcnt lgkmcnt(" #n ")" ::: "memory")
; #define PG8_BAR __builtin_amdgcn_s_barrier()
; #define PG8_SCHED __builtin_amdgcn_sched_barrier(0)
; template <class Epi>
; __device__ __forceinline__ void gemm_phase(LAS unsigned char* lds, const Gemm g, const StaticOrder& S, const Epi& E) {
;     ...
;             PG8_WAIT_V(6); PG8_BAR; PG8_MMA(1, 1, At, B1); PG8_BAR;
;             PG8_LDB(B0, 1, 0); PG8_SCHED; PG8_LDA(At, 1, 0); PG8_STAGE(PG8_SA(0, 1), a2 + hstep, voffA);
;             PG8_WAIT_L(8); PG8_BAR; PG8_WAIT_L(0); PG8_MMA(0, 0, At, B0); PG8_BAR; PG8_SCHED;
;             PG8_LDB(B1, 1, 1); PG8_STAGE(PG8_SB(1, 0), b3, voffB);
;             PG8_BAR; PG8_WAIT_L(0); PG8_MMA(0, 1, At, B1); PG8_BAR;
;             PG8_LDA(At, 1, 1); PG8_STAGE(PG8_SA(1, 0), a3, voffA);
;             PG8_BAR; PG8_WAIT_L(0); PG8_MMA(1, 0, At, B0); PG8_BAR; PG8_SCHED;
	v_mfma_f32_16x16x32_bf16 v[46:49], v[192:195], v[160:163], v[46:49]
	v_mfma_f32_16x16x32_bf16 v[42:45], v[208:211], v[160:163], v[42:45]
	v_mfma_f32_16x16x32_bf16 v[30:33], v[192:195], v[168:171], v[30:33]
	v_mfma_f32_16x16x32_bf16 v[26:29], v[208:211], v[168:171], v[26:29]
	v_mfma_f32_16x16x32_bf16 v[14:17], v[192:195], v[176:179], v[14:17]
	v_mfma_f32_16x16x32_bf16 v[10:13], v[208:211], v[176:179], v[10:13]
	v_mfma_f32_16x16x32_bf16 v[6:9], v[192:195], v[184:187], v[6:9]
	v_mfma_f32_16x16x32_bf16 v[2:5], v[208:211], v[184:187], v[2:5]
	v_mfma_f32_16x16x32_bf16 v[46:49], v[196:199], v[164:167], v[46:49]
	v_mfma_f32_16x16x32_bf16 v[42:45], v[212:215], v[164:167], v[42:45]
	v_mfma_f32_16x16x32_bf16 v[30:33], v[196:199], v[172:175], v[30:33]
	v_mfma_f32_16x16x32_bf16 v[26:29], v[212:215], v[172:175], v[26:29]
	v_mfma_f32_16x16x32_bf16 v[14:17], v[196:199], v[180:183], v[14:17]
	v_mfma_f32_16x16x32_bf16 v[10:13], v[212:215], v[180:183], v[10:13]
	v_mfma_f32_16x16x32_bf16 v[6:9], v[196:199], v[188:191], v[6:9]
	v_mfma_f32_16x16x32_bf16 v[2:5], v[212:215], v[188:191], v[2:5]
	s_barrier
	s_add_u32 s58, s58, 0x80000
	s_addc_u32 s59, s59, 0
	s_mov_b32 m0, s69
	ds_read_b128 v[160:163], v143 offset:32768
	ds_read_b128 v[164:167], v143 offset:33792
	ds_read_b128 v[168:171], v143 offset:34816
	ds_read_b128 v[172:175], v143 offset:35840
	ds_read_b128 v[176:179], v143 offset:36864
	ds_read_b128 v[180:183], v143 offset:37888
	ds_read_b128 v[184:187], v143 offset:38912
	s_add_i32 s81, 0, 0x18000
	ds_read_b128 v[188:191], v143 offset:39936
	global_load_lds_dwordx4 v134, s[58:59]
	s_mov_b32 m0, s70
	s_nop 0
	global_load_lds_dwordx4 v132, s[58:59]
	s_waitcnt lgkmcnt(8)
	s_barrier
	s_waitcnt lgkmcnt(0)
	v_mfma_f32_16x16x32_bf16 v[126:129], v[144:147], v[160:163], v[126:129]
	v_mfma_f32_16x16x32_bf16 v[122:125], v[152:155], v[160:163], v[122:125]
	v_mfma_f32_16x16x32_bf16 v[118:121], v[144:147], v[168:171], v[118:121]
	v_mfma_f32_16x16x32_bf16 v[114:117], v[152:155], v[168:171], v[114:117]
	v_mfma_f32_16x16x32_bf16 v[102:105], v[144:147], v[176:179], v[102:105]
	v_mfma_f32_16x16x32_bf16 v[98:101], v[152:155], v[176:179], v[98:101]
	v_mfma_f32_16x16x32_bf16 v[86:89], v[144:147], v[184:187], v[86:89]
	v_mfma_f32_16x16x32_bf16 v[82:85], v[152:155], v[184:187], v[82:85]
	v_mfma_f32_16x16x32_bf16 v[126:129], v[148:151], v[164:167], v[126:129]
	v_mfma_f32_16x16x32_bf16 v[122:125], v[156:159], v[164:167], v[122:125]
	v_mfma_f32_16x16x32_bf16 v[118:121], v[148:151], v[172:175], v[118:121]
	v_mfma_f32_16x16x32_bf16 v[114:117], v[156:159], v[172:175], v[114:117]
	v_mfma_f32_16x16x32_bf16 v[102:105], v[148:151], v[180:183], v[102:105]
	v_mfma_f32_16x16x32_bf16 v[98:101], v[156:159], v[180:183], v[98:101]
	v_mfma_f32_16x16x32_bf16 v[86:89], v[148:151], v[188:191], v[86:89]
	v_mfma_f32_16x16x32_bf16 v[82:85], v[156:159], v[188:191], v[82:85]
	s_barrier
	s_add_i32 s58, 0, 0x1c000
	s_add_i32 s59, s81, s64
	s_mov_b32 m0, s59
	ds_read_b128 v[192:195], v202 offset:49152
	ds_read_b128 v[196:199], v202 offset:50176
	ds_read_b128 v[208:211], v202 offset:51200
	ds_read_b128 v[212:215], v202 offset:52224
	global_load_lds_dwordx4 v0, s[98:99]
	s_add_i32 m0, s59, 0x2000
	s_nop 0
	global_load_lds_dwordx4 v130, s[98:99]
	s_barrier
	s_waitcnt lgkmcnt(0)
	v_mfma_f32_16x16x32_bf16 v[110:113], v[192:195], v[160:163], v[110:113]
	v_mfma_f32_16x16x32_bf16 v[106:109], v[208:211], v[160:163], v[106:109]
	v_mfma_f32_16x16x32_bf16 v[94:97], v[192:195], v[168:171], v[94:97]
	v_mfma_f32_16x16x32_bf16 v[90:93], v[208:211], v[168:171], v[90:93]
	v_mfma_f32_16x16x32_bf16 v[78:81], v[192:195], v[176:179], v[78:81]
	v_mfma_f32_16x16x32_bf16 v[74:77], v[208:211], v[176:179], v[74:77]
	v_mfma_f32_16x16x32_bf16 v[70:73], v[192:195], v[184:187], v[70:73]
	v_mfma_f32_16x16x32_bf16 v[66:69], v[208:211], v[184:187], v[66:69]
	v_mfma_f32_16x16x32_bf16 v[110:113], v[196:199], v[164:167], v[110:113]
	v_mfma_f32_16x16x32_bf16 v[106:109], v[212:215], v[164:167], v[106:109]
	v_mfma_f32_16x16x32_bf16 v[94:97], v[196:199], v[172:175], v[94:97]
	v_mfma_f32_16x16x32_bf16 v[90:93], v[212:215], v[172:175], v[90:93]
	v_mfma_f32_16x16x32_bf16 v[78:81], v[196:199], v[180:183], v[78:81]
	v_mfma_f32_16x16x32_bf16 v[74:77], v[212:215], v[180:183], v[74:77]
	v_mfma_f32_16x16x32_bf16 v[70:73], v[196:199], v[188:191], v[70:73]
	v_mfma_f32_16x16x32_bf16 v[66:69], v[212:215], v[188:191], v[66:69]
	s_barrier
	ds_read_b128 v[160:163], v143 offset:49152
	ds_read_b128 v[164:167], v143 offset:50176
	ds_read_b128 v[168:171], v143 offset:51200
	ds_read_b128 v[172:175], v143 offset:52224
	ds_read_b128 v[176:179], v143 offset:53248
	ds_read_b128 v[180:183], v143 offset:54272
	ds_read_b128 v[184:187], v143 offset:55296
	s_mov_b32 m0, s71
	ds_read_b128 v[188:191], v143 offset:56320
	global_load_lds_dwordx4 v134, s[100:101]
	s_mov_b32 m0, s72
	s_nop 0
	global_load_lds_dwordx4 v132, s[100:101]
	s_waitcnt vmcnt(10)
	s_barrier
	s_waitcnt lgkmcnt(0)
	v_mfma_f32_16x16x32_bf16 v[62:65], v[144:147], v[160:163], v[62:65]
	v_mfma_f32_16x16x32_bf16 v[58:61], v[152:155], v[160:163], v[58:61]
	v_mfma_f32_16x16x32_bf16 v[54:57], v[144:147], v[168:171], v[54:57]
	v_mfma_f32_16x16x32_bf16 v[50:53], v[152:155], v[168:171], v[50:53]
	v_mfma_f32_16x16x32_bf16 v[38:41], v[144:147], v[176:179], v[38:41]
	v_mfma_f32_16x16x32_bf16 v[34:37], v[152:155], v[176:179], v[34:37]
	v_mfma_f32_16x16x32_bf16 v[22:25], v[144:147], v[184:187], v[22:25]
	v_mfma_f32_16x16x32_bf16 v[18:21], v[152:155], v[184:187], v[18:21]
	v_mfma_f32_16x16x32_bf16 v[62:65], v[148:151], v[164:167], v[62:65]
	v_mfma_f32_16x16x32_bf16 v[58:61], v[156:159], v[164:167], v[58:61]
	v_mfma_f32_16x16x32_bf16 v[54:57], v[148:151], v[172:175], v[54:57]
	v_mfma_f32_16x16x32_bf16 v[50:53], v[156:159], v[172:175], v[50:53]
	v_mfma_f32_16x16x32_bf16 v[38:41], v[148:151], v[180:183], v[38:41]
	v_mfma_f32_16x16x32_bf16 v[34:37], v[156:159], v[180:183], v[34:37]
	v_mfma_f32_16x16x32_bf16 v[22:25], v[148:151], v[188:191], v[22:25]
	v_mfma_f32_16x16x32_bf16 v[18:21], v[156:159], v[188:191], v[18:21]
	s_barrier
; __device__ __forceinline__ unsigned pk2(float lo, float hi) { f32x2 v = {lo, hi}; bf16x2_t b = __builtin_convertvector(v, bf16x2_t); return __builtin_bit_cast(unsigned, b); }
; #define PG8_STAGE(bufoff, gbase, voff) do { _Pragma("unroll") for (int _i = 0; _i < 2; ++_i) \
;         __builtin_amdgcn_global_load_lds((const unsigned*)((const char*)(gbase) + (voff)[_i]), (LAS unsigned*)(lds + (bufoff) + ldsw + _i * 8192), 16, 0, 0); } while (0)
; #define PG8_MMA(ai, bj, At, Bt) do { __builtin_amdgcn_s_setprio(1); _Pragma("unroll") for (int m = 0; m < 4; ++m) _Pragma("unroll") for (int n = 0; n < 2; ++n) _Pragma("unroll") for (int k = 0; k < 2; ++k) \
;         acc[ai][bj][m][n] = __builtin_amdgcn_mfma_f32_16x16x32_bf16(Bt[n][k], At[m][k], acc[ai][bj][m][n], 0, 0, 0); __builtin_amdgcn_s_setprio(0); } while (0)
; #define PG8_WAIT_V(n) asm volatile("s_waitcnt vmcnt(" #n ")" ::: "memory")
; #define PG8_WAIT_L(n) asm volatile("s_waitcnt lgkmcnt(" #n ")" ::: "memory")
; #define PG8_BAR __builtin_amdgcn_s_barrier()
; #define PG8_SCHED __builtin_amdgcn_sched_barrier(0)
;     __device__ __forceinline__ void operator()(const AccT& acc, const Unit& u, int wr, int wc, int fr, int fq) const {
;     ...
;         } else {
; #pragma unroll
;             for (int i = 0; i < 8; ++i) rsv[i] = 1.0f;
;         }
; #pragma unroll
;         for (int ai = 0; ai < 2; ++ai)
; #pragma unroll
;             for (int m = 0; m < 4; ++m) {
;                 const int row = row0 + ai * HALF + m * 16;
;                 const float rs = rsv[ai * 4 + m];
; #pragma unroll
;                 for (int bj = 0; bj < 2; ++bj) {
;                     const f32x4 v0 = acc[ai][bj][m][0] * rs, v1 = acc[ai][bj][m][1] * rs;
;                     u32x4 w; w.x = pk2(v0[0], v0[1]); w.y = pk2(v0[2], v0[3]); w.z = pk2(v1[0], v1[1]); w.w = pk2(v1[2], v1[3]);
;                     *(u32x4*)(out + (size_t)row * ldo + col0 + bj * HALF) = w;
;                 }
; template <class Epi>
; __device__ __forceinline__ void gemm_phase(LAS unsigned char* lds, const Gemm g, const StaticOrder& S, const Epi& E) {
;     ...
;             PG8_BAR; PG8_WAIT_L(0); PG8_MMA(1, 0, At, B0); PG8_BAR; PG8_SCHED;
;             PG8_STAGE(PG8_SB(1, 1), b3 + hstep, voffB);
;             PG8_WAIT_V(6); PG8_BAR; PG8_MMA(1, 1, At, B1); PG8_BAR;
	ds_read_b128 v[144:147], v202
	ds_read_b128 v[148:151], v202 offset:1024
	ds_read_b128 v[152:155], v202 offset:2048
	s_add_i32 s80, s80, 2
	s_add_u32 s54, s54, 0x100
	s_addc_u32 s55, s55, 0
	s_add_u32 s78, s78, 0x100
	s_addc_u32 s79, s79, 0
	ds_read_b128 v[156:159], v202 offset:3072
	s_add_u32 s56, s56, 0x80080
	s_addc_u32 s57, s57, 0
	s_add_i32 s58, s58, s64
	s_mov_b32 m0, s58
	s_nop 0
	global_load_lds_dwordx4 v0, s[56:57]
	s_add_i32 m0, s58, 0x2000
	s_nop 0
	global_load_lds_dwordx4 v130, s[56:57]
	s_waitcnt vmcnt(6)
	s_barrier
	v_mfma_f32_16x16x32_bf16 v[46:49], v[192:195], v[160:163], v[46:49]
	v_mfma_f32_16x16x32_bf16 v[42:45], v[208:211], v[160:163], v[42:45]
	v_mfma_f32_16x16x32_bf16 v[30:33], v[192:195], v[168:171], v[30:33]
	v_mfma_f32_16x16x32_bf16 v[26:29], v[208:211], v[168:171], v[26:29]
	v_mfma_f32_16x16x32_bf16 v[14:17], v[192:195], v[176:179], v[14:17]
	v_mfma_f32_16x16x32_bf16 v[10:13], v[208:211], v[176:179], v[10:13]
	v_mfma_f32_16x16x32_bf16 v[6:9], v[192:195], v[184:187], v[6:9]
	v_mfma_f32_16x16x32_bf16 v[2:5], v[208:211], v[184:187], v[2:5]
	v_mfma_f32_16x16x32_bf16 v[46:49], v[196:199], v[164:167], v[46:49]
	v_mfma_f32_16x16x32_bf16 v[42:45], v[212:215], v[164:167], v[42:45]
	v_mfma_f32_16x16x32_bf16 v[30:33], v[196:199], v[172:175], v[30:33]
	v_mfma_f32_16x16x32_bf16 v[26:29], v[212:215], v[172:175], v[26:29]
	v_mfma_f32_16x16x32_bf16 v[14:17], v[196:199], v[180:183], v[14:17]
	v_mfma_f32_16x16x32_bf16 v[10:13], v[212:215], v[180:183], v[10:13]
	v_mfma_f32_16x16x32_bf16 v[6:9], v[196:199], v[188:191], v[6:9]
	v_mfma_f32_16x16x32_bf16 v[2:5], v[212:215], v[188:191], v[2:5]
	s_cmp_gt_u32 s80, 29
	s_barrier
	s_cbranch_scc0 .LBB0_77
	s_waitcnt lgkmcnt(0)
	v_lshl_add_u32 v146, s74, 8, v140
	v_lshl_or_b32 v144, s75, 8, v142
	v_ashrrev_i32_e32 v147, 31, v146
	v_ashrrev_i32_e32 v145, 31, v144
	v_cvt_pk_bf16_f32 v126, v126, v127
	v_cvt_pk_bf16_f32 v127, v128, v129
	v_cvt_pk_bf16_f32 v128, v122, v123
	v_lshlrev_b64 v[122:123], 11, v[146:147]
	v_cvt_pk_bf16_f32 v129, v124, v125
	v_lshl_add_u64 v[122:123], s[42:43], 0, v[122:123]
	v_lshlrev_b64 v[124:125], 1, v[144:145]
	v_lshl_add_u64 v[122:123], v[122:123], 0, v[124:125]
	v_cvt_pk_bf16_f32 v110, v110, v111
	v_cvt_pk_bf16_f32 v111, v112, v113
	v_cvt_pk_bf16_f32 v112, v106, v107
	v_cvt_pk_bf16_f32 v113, v108, v109
	global_store_dwordx4 v[122:123], v[110:113], off offset:256
	v_cvt_pk_bf16_f32 v94, v94, v95
	v_cvt_pk_bf16_f32 v95, v96, v97
	v_or_b32_e32 v110, 16, v146
	v_ashrrev_i32_e32 v111, 31, v110
	v_lshlrev_b64 v[110:111], 11, v[110:111]
	v_lshl_add_u64 v[110:111], s[42:43], 0, v[110:111]
	v_lshl_add_u64 v[110:111], v[110:111], 0, v[124:125]
	v_cvt_pk_bf16_f32 v96, v90, v91
	v_cvt_pk_bf16_f32 v97, v92, v93
	global_store_dwordx4 v[110:111], v[94:97], off offset:256
	s_mov_b32 s47, 0x40000
	v_cvt_pk_bf16_f32 v62, v62, v63
	v_or_b32_e32 v94, 32, v146
	v_ashrrev_i32_e32 v95, 31, v94
	v_cvt_pk_bf16_f32 v63, v64, v65
	v_cvt_pk_bf16_f32 v65, v60, v61
	s_mov_b64 s[54:55], 0x40000
	v_add_co_u32_e32 v60, vcc, s47, v122
	v_lshlrev_b64 v[94:95], 11, v[94:95]
	v_cvt_pk_bf16_f32 v64, v58, v59
	v_lshl_add_u64 v[58:59], v[122:123], 0, s[54:55]
	v_addc_co_u32_e32 v61, vcc, 0, v123, vcc
	v_cvt_pk_bf16_f32 v46, v46, v47
	v_cvt_pk_bf16_f32 v47, v48, v49
	v_cvt_pk_bf16_f32 v48, v42, v43
	v_cvt_pk_bf16_f32 v49, v44, v45
	s_mov_b32 s47, 0x48000
	v_lshl_add_u64 v[94:95], s[42:43], 0, v[94:95]
	global_store_dwordx4 v[58:59], v[46:49], off offset:256
	s_mov_b64 s[54:55], 0x48000
	v_lshl_add_u64 v[94:95], v[94:95], 0, v[124:125]
	v_add_co_u32_e32 v48, vcc, s47, v122
	v_cvt_pk_bf16_f32 v78, v78, v79
	v_cvt_pk_bf16_f32 v79, v80, v81
	v_cvt_pk_bf16_f32 v80, v74, v75
	v_cvt_pk_bf16_f32 v81, v76, v77
	v_lshl_add_u64 v[46:47], v[122:123], 0, s[54:55]
	v_addc_co_u32_e32 v49, vcc, 0, v123, vcc
	v_cvt_pk_bf16_f32 v30, v30, v31
	v_cvt_pk_bf16_f32 v31, v32, v33
	v_cvt_pk_bf16_f32 v32, v26, v27
	v_cvt_pk_bf16_f32 v33, v28, v29
	s_mov_b32 s47, 0x50000
	global_store_dwordx4 v[94:95], v[78:81], off offset:256
	global_store_dwordx4 v[46:47], v[30:33], off offset:256
	s_mov_b64 s[54:55], 0x50000
	v_or_b32_e32 v78, 48, v146
	v_add_co_u32_e32 v32, vcc, s47, v122
	v_ashrrev_i32_e32 v79, 31, v78
	v_lshl_add_u64 v[30:31], v[122:123], 0, s[54:55]
	v_addc_co_u32_e32 v33, vcc, 0, v123, vcc
	v_cvt_pk_bf16_f32 v14, v14, v15
	v_cvt_pk_bf16_f32 v15, v16, v17
	v_cvt_pk_bf16_f32 v16, v10, v11
	v_cvt_pk_bf16_f32 v17, v12, v13
	s_mov_b32 s47, 0x58000
	v_lshlrev_b64 v[78:79], 11, v[78:79]
	global_store_dwordx4 v[30:31], v[14:17], off offset:256
	v_lshl_add_u64 v[78:79], s[42:43], 0, v[78:79]
	s_mov_b64 s[54:55], 0x58000
	v_add_co_u32_e32 v16, vcc, s47, v122
	v_cvt_pk_bf16_f32 v106, v118, v119
	s_nop 0
	v_addc_co_u32_e32 v17, vcc, 0, v123, vcc
	v_cvt_pk_bf16_f32 v107, v120, v121
	v_cvt_pk_bf16_f32 v108, v114, v115
	v_cvt_pk_bf16_f32 v109, v116, v117
	v_cvt_pk_bf16_f32 v90, v102, v103
	v_cvt_pk_bf16_f32 v91, v104, v105
	v_cvt_pk_bf16_f32 v92, v98, v99
	v_cvt_pk_bf16_f32 v93, v100, v101
	v_cvt_pk_bf16_f32 v74, v86, v87
	v_cvt_pk_bf16_f32 v75, v88, v89
	v_cvt_pk_bf16_f32 v76, v82, v83
	v_cvt_pk_bf16_f32 v77, v84, v85
	v_lshl_add_u64 v[78:79], v[78:79], 0, v[124:125]
	v_cvt_pk_bf16_f32 v70, v70, v71
	v_cvt_pk_bf16_f32 v71, v72, v73
	v_cvt_pk_bf16_f32 v72, v66, v67
	v_cvt_pk_bf16_f32 v73, v68, v69
	v_cvt_pk_bf16_f32 v42, v54, v55
	v_cvt_pk_bf16_f32 v43, v56, v57
	v_cvt_pk_bf16_f32 v44, v50, v51
	v_cvt_pk_bf16_f32 v45, v52, v53
	v_cvt_pk_bf16_f32 v26, v38, v39
	v_cvt_pk_bf16_f32 v27, v40, v41
	v_cvt_pk_bf16_f32 v28, v34, v35
	v_cvt_pk_bf16_f32 v29, v36, v37
	v_cvt_pk_bf16_f32 v10, v22, v23
	v_cvt_pk_bf16_f32 v11, v24, v25
	v_cvt_pk_bf16_f32 v12, v18, v19
	v_cvt_pk_bf16_f32 v13, v20, v21
	v_lshl_add_u64 v[14:15], v[122:123], 0, s[54:55]
	v_cvt_pk_bf16_f32 v6, v6, v7
	v_cvt_pk_bf16_f32 v7, v8, v9
	v_cvt_pk_bf16_f32 v8, v2, v3
	v_cvt_pk_bf16_f32 v9, v4, v5
	s_and_b64 vcc, exec, s[44:45]
	s_mov_b32 s75, s46
	s_mov_b32 s74, s48
	s_mov_b64 s[56:57], s[52:53]
	s_mov_b64 s[54:55], s[50:51]
	global_store_dwordx4 v[122:123], v[126:129], off
	global_store_dwordx4 v[110:111], v[106:109], off
	global_store_dwordx4 v[94:95], v[90:93], off
	global_store_dwordx4 v[78:79], v[74:77], off
	global_store_dwordx4 v[78:79], v[70:73], off offset:256
	global_store_dwordx4 v[60:61], v[62:65], off
	global_store_dwordx4 v[48:49], v[42:45], off
	global_store_dwordx4 v[32:33], v[26:29], off
	global_store_dwordx4 v[16:17], v[10:13], off
	global_store_dwordx4 v[14:15], v[6:9], off offset:256
	s_cbranch_vccz .LBB0_74
	s_waitcnt vmcnt(0)
	s_cmpk_gt_u32 s60, 0xff
	s_cbranch_scc1 .LBB0_81
	s_barrier

; #define PG8_STAGE(bufoff, gbase, voff) do { _Pragma("unroll") for (int _i = 0; _i < 2; ++_i) \
;         __builtin_amdgcn_global_load_lds((const unsigned*)((const char*)(gbase) + (voff)[_i]), (LAS unsigned*)(lds + (bufoff) + ldsw + _i * 8192), 16, 0, 0); } while (0)
; #define PG8_LDA(dst, b, h) do { _Pragma("unroll") for (int m = 0; m < 4; ++m) _Pragma("unroll") for (int k = 0; k < 2; ++k) dst[m][k] = *(const LAS bf16x8*)(lds + PG8_SA(b, h) + aoff + m * 2048 + k * 1024); } while (0)
; #define PG8_LDB(dst, b, h) do { _Pragma("unroll") for (int n = 0; n < 2; ++n) _Pragma("unroll") for (int k = 0; k < 2; ++k) dst[n][k] = *(const LAS bf16x8*)(lds + PG8_SB(b, h) + boff + n * 2048 + k * 1024); } while (0)
; #define PG8_MMA(ai, bj, At, Bt) do { __builtin_amdgcn_s_setprio(1); _Pragma("unroll") for (int m = 0; m < 4; ++m) _Pragma("unroll") for (int n = 0; n < 2; ++n) _Pragma("unroll") for (int k = 0; k < 2; ++k) \
;         acc[ai][bj][m][n] = __builtin_amdgcn_mfma_f32_16x16x32_bf16(Bt[n][k], At[m][k], acc[ai][bj][m][n], 0, 0, 0); __builtin_amdgcn_s_setprio(0); } while (0)
; #define PG8_WAIT_V(n) asm volatile("s_waitcnt vmcnt(" #n ")" ::: "memory")
; #define PG8_WAIT_L(n) asm volatile("s_waitcnt lgkmcnt(" #n ")" ::: "memory")
; template <class Epi>
; __device__ __forceinline__ void gemm_phase(LAS unsigned char* lds, const Gemm g, const StaticOrder& S, const Epi& E) {
;     ...
;         for (int t = 0; t < nt; t += 2) {
;             const bool last = (t == nt - 2);
;             const char* a1 = cA + (size_t)(t + 1) * kstep;
;             const char* a2 = last ? nA : cA + (size_t)(t + 2) * kstep; const char* b2 = last ? nB : cB + (size_t)(t + 2) * kstep;
;             const char* a3 = a2 + kstep; const char* b3 = b2 + kstep;
;             PG8_LDB(B0, 0, 0); PG8_SCHED; PG8_LDA(At, 0, 0); PG8_STAGE(PG8_SA(1, 1), a1 + hstep, voffA);
;             PG8_WAIT_L(8); PG8_BAR; PG8_WAIT_L(0); PG8_MMA(0, 0, At, B0); PG8_BAR; PG8_SCHED;
;             PG8_LDB(B1, 0, 1); PG8_STAGE(PG8_SB(0, 0), b2, voffB);
;             PG8_BAR; PG8_WAIT_L(0); PG8_MMA(0, 1, At, B1); PG8_BAR;
;             PG8_LDA(At, 0, 1); PG8_STAGE(PG8_SA(0, 0), a2, voffA);
;             PG8_BAR; PG8_WAIT_L(0); PG8_MMA(1, 0, At, B0); PG8_BAR; PG8_SCHED;
;             PG8_STAGE(PG8_SB(0, 1), b2 + hstep, voffB);
;             PG8_WAIT_V(6); PG8_BAR; PG8_MMA(1, 1, At, B1); PG8_BAR;
.LBB0_90:
	s_add_u32 s48, s46, 0xfff80080
	s_addc_u32 s49, s47, -1
	s_add_i32 s74, 0, 0x10000
	s_cmp_eq_u32 s73, 28
	s_cselect_b32 s51, s41, s49
	s_cselect_b32 s50, s69, s48
	s_cselect_b32 s49, s39, s72
	s_cselect_b32 s48, s70, s71
	s_add_i32 m0, s56, 0xc000
	ds_read_b128 v[168:171], v151
	ds_read_b128 v[172:175], v151 offset:1024
	ds_read_b128 v[176:179], v151 offset:2048
	ds_read_b128 v[180:183], v151 offset:3072
	ds_read_b128 v[184:187], v151 offset:4096
	ds_read_b128 v[188:191], v151 offset:5120
	ds_read_b128 v[192:195], v151 offset:6144
	ds_read_b128 v[196:199], v151 offset:7168
	global_load_lds_dwordx4 v136, s[46:47]
	s_add_i32 m0, s56, 0xe000
	s_nop 0
	global_load_lds_dwordx4 v138, s[46:47]
	s_waitcnt lgkmcnt(8)
	s_barrier
	s_waitcnt lgkmcnt(0)
	v_mfma_f32_16x16x32_bf16 v[126:129], v[152:155], v[168:171], v[126:129]
	v_mfma_f32_16x16x32_bf16 v[122:125], v[160:163], v[168:171], v[122:125]
	v_mfma_f32_16x16x32_bf16 v[110:113], v[152:155], v[176:179], v[110:113]
	v_mfma_f32_16x16x32_bf16 v[102:105], v[160:163], v[176:179], v[102:105]
	v_mfma_f32_16x16x32_bf16 v[94:97], v[152:155], v[184:187], v[94:97]
	v_mfma_f32_16x16x32_bf16 v[86:89], v[160:163], v[184:187], v[86:89]
	v_mfma_f32_16x16x32_bf16 v[78:81], v[152:155], v[192:195], v[78:81]
	v_mfma_f32_16x16x32_bf16 v[70:73], v[160:163], v[192:195], v[70:73]
	v_mfma_f32_16x16x32_bf16 v[126:129], v[156:159], v[172:175], v[126:129]
	v_mfma_f32_16x16x32_bf16 v[122:125], v[164:167], v[172:175], v[122:125]
	v_mfma_f32_16x16x32_bf16 v[110:113], v[156:159], v[180:183], v[110:113]
	v_mfma_f32_16x16x32_bf16 v[102:105], v[164:167], v[180:183], v[102:105]
	v_mfma_f32_16x16x32_bf16 v[94:97], v[156:159], v[188:191], v[94:97]
	v_mfma_f32_16x16x32_bf16 v[86:89], v[164:167], v[188:191], v[86:89]
	v_mfma_f32_16x16x32_bf16 v[78:81], v[156:159], v[196:199], v[78:81]
	v_mfma_f32_16x16x32_bf16 v[70:73], v[164:167], v[196:199], v[70:73]
	s_barrier
	s_add_i32 s76, 0, 0x14000
	s_add_i32 s74, s74, s55
	s_mov_b32 m0, s74
	ds_read_b128 v[208:211], v200 offset:16384
	ds_read_b128 v[212:215], v200 offset:17408
	ds_read_b128 v[216:219], v200 offset:18432
	ds_read_b128 v[220:223], v200 offset:19456
	global_load_lds_dwordx4 v0, s[48:49]
	s_add_i32 m0, s74, 0x2000
	s_add_u32 s98, s48, s22
	global_load_lds_dwordx4 v130, s[48:49]
	s_addc_u32 s99, s49, s23
	s_barrier
	s_waitcnt lgkmcnt(0)
	v_mfma_f32_16x16x32_bf16 v[118:121], v[208:211], v[168:171], v[118:121]
	v_mfma_f32_16x16x32_bf16 v[114:117], v[216:219], v[168:171], v[114:117]
	v_mfma_f32_16x16x32_bf16 v[106:109], v[208:211], v[176:179], v[106:109]
	v_mfma_f32_16x16x32_bf16 v[98:101], v[216:219], v[176:179], v[98:101]
	v_mfma_f32_16x16x32_bf16 v[90:93], v[208:211], v[184:187], v[90:93]
	v_mfma_f32_16x16x32_bf16 v[82:85], v[216:219], v[184:187], v[82:85]
	v_mfma_f32_16x16x32_bf16 v[74:77], v[208:211], v[192:195], v[74:77]
	v_mfma_f32_16x16x32_bf16 v[66:69], v[216:219], v[192:195], v[66:69]
	v_mfma_f32_16x16x32_bf16 v[118:121], v[212:215], v[172:175], v[118:121]
	v_mfma_f32_16x16x32_bf16 v[114:117], v[220:223], v[172:175], v[114:117]
	v_mfma_f32_16x16x32_bf16 v[106:109], v[212:215], v[180:183], v[106:109]
	v_mfma_f32_16x16x32_bf16 v[98:101], v[220:223], v[180:183], v[98:101]
	v_mfma_f32_16x16x32_bf16 v[90:93], v[212:215], v[188:191], v[90:93]
	v_mfma_f32_16x16x32_bf16 v[82:85], v[220:223], v[188:191], v[82:85]
	v_mfma_f32_16x16x32_bf16 v[74:77], v[212:215], v[196:199], v[74:77]
	v_mfma_f32_16x16x32_bf16 v[66:69], v[220:223], v[196:199], v[66:69]
	s_barrier
	ds_read_b128 v[168:171], v151 offset:16384
	ds_read_b128 v[172:175], v151 offset:17408
	ds_read_b128 v[176:179], v151 offset:18432
	ds_read_b128 v[180:183], v151 offset:19456
	ds_read_b128 v[184:187], v151 offset:20480
	ds_read_b128 v[188:191], v151 offset:21504
	ds_read_b128 v[192:195], v151 offset:22528
	s_mov_b32 m0, s56
	s_add_u32 s100, s50, s22
	s_addc_u32 s101, s51, s23
	ds_read_b128 v[196:199], v151 offset:23552
	global_load_lds_dwordx4 v134, s[50:51]
	s_mov_b32 m0, s57
	s_nop 0
	global_load_lds_dwordx4 v132, s[50:51]
	s_waitcnt vmcnt(10)
	s_barrier
	s_waitcnt lgkmcnt(0)
	v_mfma_f32_16x16x32_bf16 v[62:65], v[152:155], v[168:171], v[62:65]
	v_mfma_f32_16x16x32_bf16 v[54:57], v[160:163], v[168:171], v[54:57]
	v_mfma_f32_16x16x32_bf16 v[46:49], v[152:155], v[176:179], v[46:49]
	v_mfma_f32_16x16x32_bf16 v[38:41], v[160:163], v[176:179], v[38:41]
	v_mfma_f32_16x16x32_bf16 v[30:33], v[152:155], v[184:187], v[30:33]
	v_mfma_f32_16x16x32_bf16 v[22:25], v[160:163], v[184:187], v[22:25]
	v_mfma_f32_16x16x32_bf16 v[14:17], v[152:155], v[192:195], v[14:17]
	v_mfma_f32_16x16x32_bf16 v[6:9], v[160:163], v[192:195], v[6:9]
	v_mfma_f32_16x16x32_bf16 v[62:65], v[156:159], v[172:175], v[62:65]
	v_mfma_f32_16x16x32_bf16 v[54:57], v[164:167], v[172:175], v[54:57]
	v_mfma_f32_16x16x32_bf16 v[46:49], v[156:159], v[180:183], v[46:49]
	v_mfma_f32_16x16x32_bf16 v[38:41], v[164:167], v[180:183], v[38:41]
	v_mfma_f32_16x16x32_bf16 v[30:33], v[156:159], v[188:191], v[30:33]
	v_mfma_f32_16x16x32_bf16 v[22:25], v[164:167], v[188:191], v[22:25]
	v_mfma_f32_16x16x32_bf16 v[14:17], v[156:159], v[196:199], v[14:17]
	v_mfma_f32_16x16x32_bf16 v[6:9], v[164:167], v[196:199], v[6:9]
	s_barrier
	ds_read_b128 v[152:155], v200 offset:32768
	ds_read_b128 v[156:159], v200 offset:33792
	ds_read_b128 v[160:163], v200 offset:34816
	ds_read_b128 v[164:167], v200 offset:35840
	s_add_u32 s74, s48, 0x80000
	s_addc_u32 s75, s49, 0
	s_add_i32 s76, s76, s55
	s_mov_b32 m0, s76
	s_nop 0
	global_load_lds_dwordx4 v0, s[74:75]
	s_add_i32 m0, s76, 0x2000
	s_nop 0
	global_load_lds_dwordx4 v130, s[74:75]
	s_waitcnt vmcnt(6)
	s_barrier
; #define PG8_STAGE(bufoff, gbase, voff) do { _Pragma("unroll") for (int _i = 0; _i < 2; ++_i) \
;         __builtin_amdgcn_global_load_lds((const unsigned*)((const char*)(gbase) + (voff)[_i]), (LAS unsigned*)(lds + (bufoff) + ldsw + _i * 8192), 16, 0, 0); } while (0)
; #define PG8_LDA(dst, b, h) do { _Pragma("unroll") for (int m = 0; m < 4; ++m) _Pragma("unroll") for (int k = 0; k < 2; ++k) dst[m][k] = *(const LAS bf16x8*)(lds + PG8_SA(b, h) + aoff + m * 2048 + k * 1024); } while (0)
; #define PG8_LDB(dst, b, h) do { _Pragma("unroll") for (int n = 0; n < 2; ++n) _Pragma("unroll") for (int k = 0; k < 2; ++k) dst[n][k] = *(const LAS bf16x8*)(lds + PG8_SB(b, h) + boff + n * 2048 + k * 1024); } while (0)
; #define PG8_MMA(ai, bj, At, Bt) do { __builtin_amdgcn_s_setprio(1); _Pragma("unroll") for (int m = 0; m < 4; ++m) _Pragma("unroll") for (int n = 0; n < 2; ++n) _Pragma("unroll") for (int k = 0; k < 2; ++k) \
;         acc[ai][bj][m][n] = __builtin_amdgcn_mfma_f32_16x16x32_bf16(Bt[n][k], At[m][k], acc[ai][bj][m][n], 0, 0, 0); __builtin_amdgcn_s_setprio(0); } while (0)
; #define PG8_WAIT_V(n) asm volatile("s_waitcnt vmcnt(" #n ")" ::: "memory")
; #define PG8_WAIT_L(n) asm volatile("s_waitcnt lgkmcnt(" #n ")" ::: "memory")
; #define PG8_BAR __builtin_amdgcn_s_barrier()
; #define PG8_SCHED __builtin_amdgcn_sched_barrier(0)
; template <class Epi>
; __device__ __forceinline__ void gemm_phase(LAS unsigned char* lds, const Gemm g, const StaticOrder& S, const Epi& E) {
;     ...
;             PG8_WAIT_V(6); PG8_BAR; PG8_MMA(1, 1, At, B1); PG8_BAR;
;             PG8_LDB(B0, 1, 0); PG8_SCHED; PG8_LDA(At, 1, 0); PG8_STAGE(PG8_SA(0, 1), a2 + hstep, voffA);
;             PG8_WAIT_L(8); PG8_BAR; PG8_WAIT_L(0); PG8_MMA(0, 0, At, B0); PG8_BAR; PG8_SCHED;
;             PG8_LDB(B1, 1, 1); PG8_STAGE(PG8_SB(1, 0), b3, voffB);
;             PG8_BAR; PG8_WAIT_L(0); PG8_MMA(0, 1, At, B1); PG8_BAR;
;             PG8_LDA(At, 1, 1); PG8_STAGE(PG8_SA(1, 0), a3, voffA);
;             PG8_BAR; PG8_WAIT_L(0); PG8_MMA(1, 0, At, B0); PG8_BAR; PG8_SCHED;
	v_mfma_f32_16x16x32_bf16 v[58:61], v[208:211], v[168:171], v[58:61]
	v_mfma_f32_16x16x32_bf16 v[50:53], v[216:219], v[168:171], v[50:53]
	v_mfma_f32_16x16x32_bf16 v[42:45], v[208:211], v[176:179], v[42:45]
	v_mfma_f32_16x16x32_bf16 v[34:37], v[216:219], v[176:179], v[34:37]
	v_mfma_f32_16x16x32_bf16 v[26:29], v[208:211], v[184:187], v[26:29]
	v_mfma_f32_16x16x32_bf16 v[18:21], v[216:219], v[184:187], v[18:21]
	v_mfma_f32_16x16x32_bf16 v[10:13], v[208:211], v[192:195], v[10:13]
	v_mfma_f32_16x16x32_bf16 v[2:5], v[216:219], v[192:195], v[2:5]
	v_mfma_f32_16x16x32_bf16 v[58:61], v[212:215], v[172:175], v[58:61]
	v_mfma_f32_16x16x32_bf16 v[50:53], v[220:223], v[172:175], v[50:53]
	v_mfma_f32_16x16x32_bf16 v[42:45], v[212:215], v[180:183], v[42:45]
	v_mfma_f32_16x16x32_bf16 v[34:37], v[220:223], v[180:183], v[34:37]
	v_mfma_f32_16x16x32_bf16 v[26:29], v[212:215], v[188:191], v[26:29]
	v_mfma_f32_16x16x32_bf16 v[18:21], v[220:223], v[188:191], v[18:21]
	v_mfma_f32_16x16x32_bf16 v[10:13], v[212:215], v[196:199], v[10:13]
	v_mfma_f32_16x16x32_bf16 v[2:5], v[220:223], v[196:199], v[2:5]
	s_barrier
	s_add_u32 s50, s50, 0x80000
	s_addc_u32 s51, s51, 0
	s_mov_b32 m0, s58
	ds_read_b128 v[168:171], v151 offset:32768
	ds_read_b128 v[172:175], v151 offset:33792
	ds_read_b128 v[176:179], v151 offset:34816
	ds_read_b128 v[180:183], v151 offset:35840
	ds_read_b128 v[184:187], v151 offset:36864
	ds_read_b128 v[188:191], v151 offset:37888
	ds_read_b128 v[192:195], v151 offset:38912
	s_add_i32 s74, 0, 0x18000
	ds_read_b128 v[196:199], v151 offset:39936
	global_load_lds_dwordx4 v134, s[50:51]
	s_mov_b32 m0, s59
	s_nop 0
	global_load_lds_dwordx4 v132, s[50:51]
	s_waitcnt lgkmcnt(8)
	s_barrier
	s_waitcnt lgkmcnt(0)
	v_mfma_f32_16x16x32_bf16 v[126:129], v[152:155], v[168:171], v[126:129]
	v_mfma_f32_16x16x32_bf16 v[122:125], v[160:163], v[168:171], v[122:125]
	v_mfma_f32_16x16x32_bf16 v[110:113], v[152:155], v[176:179], v[110:113]
	v_mfma_f32_16x16x32_bf16 v[102:105], v[160:163], v[176:179], v[102:105]
	v_mfma_f32_16x16x32_bf16 v[94:97], v[152:155], v[184:187], v[94:97]
	v_mfma_f32_16x16x32_bf16 v[86:89], v[160:163], v[184:187], v[86:89]
	v_mfma_f32_16x16x32_bf16 v[78:81], v[152:155], v[192:195], v[78:81]
	v_mfma_f32_16x16x32_bf16 v[70:73], v[160:163], v[192:195], v[70:73]
	v_mfma_f32_16x16x32_bf16 v[126:129], v[156:159], v[172:175], v[126:129]
	v_mfma_f32_16x16x32_bf16 v[122:125], v[164:167], v[172:175], v[122:125]
	v_mfma_f32_16x16x32_bf16 v[110:113], v[156:159], v[180:183], v[110:113]
	v_mfma_f32_16x16x32_bf16 v[102:105], v[164:167], v[180:183], v[102:105]
	v_mfma_f32_16x16x32_bf16 v[94:97], v[156:159], v[188:191], v[94:97]
	v_mfma_f32_16x16x32_bf16 v[86:89], v[164:167], v[188:191], v[86:89]
	v_mfma_f32_16x16x32_bf16 v[78:81], v[156:159], v[196:199], v[78:81]
	v_mfma_f32_16x16x32_bf16 v[70:73], v[164:167], v[196:199], v[70:73]
	s_barrier
	s_add_i32 s50, 0, 0x1c000
	s_add_i32 s51, s74, s55
	s_mov_b32 m0, s51
	ds_read_b128 v[208:211], v200 offset:49152
	ds_read_b128 v[212:215], v200 offset:50176
	ds_read_b128 v[216:219], v200 offset:51200
	ds_read_b128 v[220:223], v200 offset:52224
	global_load_lds_dwordx4 v0, s[98:99]
	s_add_i32 m0, s51, 0x2000
	s_nop 0
	global_load_lds_dwordx4 v130, s[98:99]
	s_barrier
	s_waitcnt lgkmcnt(0)
	v_mfma_f32_16x16x32_bf16 v[118:121], v[208:211], v[168:171], v[118:121]
	v_mfma_f32_16x16x32_bf16 v[114:117], v[216:219], v[168:171], v[114:117]
	v_mfma_f32_16x16x32_bf16 v[106:109], v[208:211], v[176:179], v[106:109]
	v_mfma_f32_16x16x32_bf16 v[98:101], v[216:219], v[176:179], v[98:101]
	v_mfma_f32_16x16x32_bf16 v[90:93], v[208:211], v[184:187], v[90:93]
	v_mfma_f32_16x16x32_bf16 v[82:85], v[216:219], v[184:187], v[82:85]
	v_mfma_f32_16x16x32_bf16 v[74:77], v[208:211], v[192:195], v[74:77]
	v_mfma_f32_16x16x32_bf16 v[66:69], v[216:219], v[192:195], v[66:69]
	v_mfma_f32_16x16x32_bf16 v[118:121], v[212:215], v[172:175], v[118:121]
	v_mfma_f32_16x16x32_bf16 v[114:117], v[220:223], v[172:175], v[114:117]
	v_mfma_f32_16x16x32_bf16 v[106:109], v[212:215], v[180:183], v[106:109]
	v_mfma_f32_16x16x32_bf16 v[98:101], v[220:223], v[180:183], v[98:101]
	v_mfma_f32_16x16x32_bf16 v[90:93], v[212:215], v[188:191], v[90:93]
	v_mfma_f32_16x16x32_bf16 v[82:85], v[220:223], v[188:191], v[82:85]
	v_mfma_f32_16x16x32_bf16 v[74:77], v[212:215], v[196:199], v[74:77]
	v_mfma_f32_16x16x32_bf16 v[66:69], v[220:223], v[196:199], v[66:69]
	s_barrier
	ds_read_b128 v[168:171], v151 offset:49152
	ds_read_b128 v[172:175], v151 offset:50176
	ds_read_b128 v[176:179], v151 offset:51200
	ds_read_b128 v[180:183], v151 offset:52224
	ds_read_b128 v[184:187], v151 offset:53248
	ds_read_b128 v[188:191], v151 offset:54272
	ds_read_b128 v[192:195], v151 offset:55296
	s_mov_b32 m0, s61
	ds_read_b128 v[196:199], v151 offset:56320
	global_load_lds_dwordx4 v134, s[100:101]
	s_mov_b32 m0, s63
	s_nop 0
	global_load_lds_dwordx4 v132, s[100:101]
	s_waitcnt vmcnt(10)
	s_barrier
	s_waitcnt lgkmcnt(0)
	v_mfma_f32_16x16x32_bf16 v[62:65], v[152:155], v[168:171], v[62:65]
	v_mfma_f32_16x16x32_bf16 v[54:57], v[160:163], v[168:171], v[54:57]
	v_mfma_f32_16x16x32_bf16 v[46:49], v[152:155], v[176:179], v[46:49]
	v_mfma_f32_16x16x32_bf16 v[38:41], v[160:163], v[176:179], v[38:41]
	v_mfma_f32_16x16x32_bf16 v[30:33], v[152:155], v[184:187], v[30:33]
	v_mfma_f32_16x16x32_bf16 v[22:25], v[160:163], v[184:187], v[22:25]
	v_mfma_f32_16x16x32_bf16 v[14:17], v[152:155], v[192:195], v[14:17]
	v_mfma_f32_16x16x32_bf16 v[6:9], v[160:163], v[192:195], v[6:9]
	v_mfma_f32_16x16x32_bf16 v[62:65], v[156:159], v[172:175], v[62:65]
	v_mfma_f32_16x16x32_bf16 v[54:57], v[164:167], v[172:175], v[54:57]
	v_mfma_f32_16x16x32_bf16 v[46:49], v[156:159], v[180:183], v[46:49]
	v_mfma_f32_16x16x32_bf16 v[38:41], v[164:167], v[180:183], v[38:41]
	v_mfma_f32_16x16x32_bf16 v[30:33], v[156:159], v[188:191], v[30:33]
	v_mfma_f32_16x16x32_bf16 v[22:25], v[164:167], v[188:191], v[22:25]
	v_mfma_f32_16x16x32_bf16 v[14:17], v[156:159], v[196:199], v[14:17]
	v_mfma_f32_16x16x32_bf16 v[6:9], v[164:167], v[196:199], v[6:9]
	s_barrier
; #define PG8_STAGE(bufoff, gbase, voff) do { _Pragma("unroll") for (int _i = 0; _i < 2; ++_i) \
;         __builtin_amdgcn_global_load_lds((const unsigned*)((const char*)(gbase) + (voff)[_i]), (LAS unsigned*)(lds + (bufoff) + ldsw + _i * 8192), 16, 0, 0); } while (0)
; #define PG8_MMA(ai, bj, At, Bt) do { __builtin_amdgcn_s_setprio(1); _Pragma("unroll") for (int m = 0; m < 4; ++m) _Pragma("unroll") for (int n = 0; n < 2; ++n) _Pragma("unroll") for (int k = 0; k < 2; ++k) \
;         acc[ai][bj][m][n] = __builtin_amdgcn_mfma_f32_16x16x32_bf16(Bt[n][k], At[m][k], acc[ai][bj][m][n], 0, 0, 0); __builtin_amdgcn_s_setprio(0); } while (0)
; #define PG8_WAIT_V(n) asm volatile("s_waitcnt vmcnt(" #n ")" ::: "memory")
; #define PG8_WAIT_L(n) asm volatile("s_waitcnt lgkmcnt(" #n ")" ::: "memory")
; #define PG8_BAR __builtin_amdgcn_s_barrier()
; #define PG8_SCHED __builtin_amdgcn_sched_barrier(0)
;     __device__ __forceinline__ void operator()(const AccT& acc, const Unit& u, int wr, int wc, int fr, int fq) const {
;     ...
;         {
;             const int ln = (fq << 4) | fr;
;             float sa = ss[u.pm * BM + wr * 64 + ln], sb = ss[u.pm * BM + HALF + wr * 64 + ln];
;             sa = __builtin_amdgcn_rsqf(sa * (1.0f / DM) + EPS); sb = __builtin_amdgcn_rsqf(sb * (1.0f / DM) + EPS);
; #pragma unroll
;             for (int m = 0; m < 4; ++m) { rsv[m] = __shfl(sa, 16 * m + fr); rsv[4 + m] = __shfl(sb, 16 * m + fr); }
;         }
; #pragma unroll
;         for (int ai = 0; ai < 2; ++ai)
; #pragma unroll
;             for (int m = 0; m < 4; ++m) {
;                 const int row = row0 + ai * HALF + m * 16;
;                 const float rs = rsv[ai * 4 + m];
;                 float v[8];
; #pragma unroll
;                 for (int n = 0; n < 2; ++n)
; #pragma unroll
;                     for (int j = 0; j < 4; ++j) {
;                         const float g = acc[ai][0][m][n][j] * rs, up = acc[ai][1][m][n][j] * rs;
;                         const float sg = __builtin_amdgcn_rcpf(1.0f + __builtin_amdgcn_exp2f(-g * LOG2E));
; template <class Epi>
; __device__ __forceinline__ void gemm_phase(LAS unsigned char* lds, const Gemm g, const StaticOrder& S, const Epi& E) {
;     ...
;             PG8_BAR; PG8_WAIT_L(0); PG8_MMA(1, 0, At, B0); PG8_BAR; PG8_SCHED;
;             PG8_STAGE(PG8_SB(1, 1), b3 + hstep, voffB);
;             PG8_WAIT_V(6); PG8_BAR; PG8_MMA(1, 1, At, B1); PG8_BAR;
	ds_read_b128 v[152:155], v200
	ds_read_b128 v[156:159], v200 offset:1024
	ds_read_b128 v[160:163], v200 offset:2048
	s_add_i32 s73, s73, 2
	s_add_u32 s46, s46, 0x100
	s_addc_u32 s47, s47, 0
	s_add_u32 s71, s71, 0x100
	s_addc_u32 s72, s72, 0
	ds_read_b128 v[164:167], v200 offset:3072
	s_add_u32 s48, s48, 0x80080
	s_addc_u32 s49, s49, 0
	s_add_i32 s50, s50, s55
	s_mov_b32 m0, s50
	s_nop 0
	global_load_lds_dwordx4 v0, s[48:49]
	s_add_i32 m0, s50, 0x2000
	s_nop 0
	global_load_lds_dwordx4 v130, s[48:49]
	s_waitcnt vmcnt(6)
	s_barrier
	v_mfma_f32_16x16x32_bf16 v[58:61], v[208:211], v[168:171], v[58:61]
	v_mfma_f32_16x16x32_bf16 v[50:53], v[216:219], v[168:171], v[50:53]
	v_mfma_f32_16x16x32_bf16 v[42:45], v[208:211], v[176:179], v[42:45]
	v_mfma_f32_16x16x32_bf16 v[34:37], v[216:219], v[176:179], v[34:37]
	v_mfma_f32_16x16x32_bf16 v[26:29], v[208:211], v[184:187], v[26:29]
	v_mfma_f32_16x16x32_bf16 v[18:21], v[216:219], v[184:187], v[18:21]
	v_mfma_f32_16x16x32_bf16 v[10:13], v[208:211], v[192:195], v[10:13]
	v_mfma_f32_16x16x32_bf16 v[2:5], v[216:219], v[192:195], v[2:5]
	v_mfma_f32_16x16x32_bf16 v[58:61], v[212:215], v[172:175], v[58:61]
	v_mfma_f32_16x16x32_bf16 v[50:53], v[220:223], v[172:175], v[50:53]
	v_mfma_f32_16x16x32_bf16 v[42:45], v[212:215], v[180:183], v[42:45]
	v_mfma_f32_16x16x32_bf16 v[34:37], v[220:223], v[180:183], v[34:37]
	v_mfma_f32_16x16x32_bf16 v[26:29], v[212:215], v[188:191], v[26:29]
	v_mfma_f32_16x16x32_bf16 v[18:21], v[220:223], v[188:191], v[18:21]
	v_mfma_f32_16x16x32_bf16 v[10:13], v[212:215], v[196:199], v[10:13]
	v_mfma_f32_16x16x32_bf16 v[2:5], v[220:223], v[196:199], v[2:5]
	s_cmp_gt_u32 s73, 29
	s_barrier
	s_cbranch_scc0 .LBB0_90
	s_waitcnt lgkmcnt(0)
	s_lshl_b32 s39, s68, 8
	s_add_i32 s39, s39, s60
	v_or_b32_e32 v154, s39, v145
	v_ashrrev_i32_e32 v155, 31, v154
	v_lshl_add_u64 v[154:155], v[154:155], 2, s[2:3]
	global_load_dword v140, v[154:155], off
	v_add_u32_e32 v154, s39, v147
	v_ashrrev_i32_e32 v155, 31, v154
	v_lshl_add_u64 v[154:155], v[154:155], 2, s[2:3]
	global_load_dword v142, v[154:155], off
	v_readlane_b32 s46, v251, 58
	v_readlane_b32 s47, v251, 59
	v_or_b32_e32 v153, s39, v141
	s_movk_i32 s39, 0x2c00
	s_and_b64 vcc, exec, s[36:37]
	s_mov_b32 s68, s40
	s_mov_b64 s[48:49], s[44:45]
	s_waitcnt vmcnt(0)
	v_fmamk_f32 v140, v140, 0x3a000000, v233
	v_rsq_f32_e32 v140, v140
	v_fmamk_f32 v142, v142, 0x3a000000, v233
	v_rsq_f32_e32 v154, v142
	v_and_or_b32 v142, v234, 64, v141
	v_lshlrev_b32_e32 v155, 2, v142
	ds_bpermute_b32 v156, v155, v140
	ds_bpermute_b32 v152, v155, v140 offset:64
	ds_bpermute_b32 v146, v155, v154
	ds_bpermute_b32 v144, v155, v154 offset:64
	ds_bpermute_b32 v150, v155, v140 offset:128
	s_waitcnt lgkmcnt(0)
	v_pk_mul_f32 v[126:127], v[126:127], v[156:157] op_sel_hi:[1,0]
	ds_bpermute_b32 v142, v155, v154 offset:128
	v_mul_f32_e32 v157, 0xbfb8aa3b, v126
	v_exp_f32_e32 v157, v157
	ds_bpermute_b32 v148, v155, v140 offset:192
	ds_bpermute_b32 v140, v155, v154 offset:192
	v_lshl_or_b32 v154, s65, 7, v149
	v_add_f32_e32 v157, 1.0, v157
	v_rcp_f32_e32 v158, v157
	v_pk_mul_f32 v[118:119], v[118:119], v[156:157] op_sel_hi:[1,0]
	v_mul_f32_e32 v157, 0xbfb8aa3b, v127
	v_exp_f32_e32 v157, v157
	v_ashrrev_i32_e32 v155, 31, v154
	v_pk_mul_f32 v[110:111], v[110:111], v[152:153] op_sel_hi:[1,0]
	v_pk_mul_f32 v[106:107], v[106:107], v[152:153] op_sel_hi:[1,0]
	v_add_f32_e32 v157, 1.0, v157
	v_rcp_f32_e32 v159, v157
	v_pk_mul_f32 v[120:121], v[120:121], v[156:157] op_sel_hi:[1,0]
	v_pk_mul_f32 v[122:123], v[122:123], v[156:157] op_sel_hi:[1,0]
	v_pk_mul_f32 v[114:115], v[114:115], v[156:157] op_sel_hi:[1,0]
	v_pk_mul_f32 v[126:127], v[126:127], v[158:159]
	v_pk_mul_f32 v[116:117], v[116:117], v[156:157] op_sel_hi:[1,0]
	v_pk_mul_f32 v[118:119], v[118:119], v[126:127]
	v_pk_mul_f32 v[126:127], v[128:129], v[156:157] op_sel_hi:[1,0]
	v_pk_mul_f32 v[108:109], v[108:109], v[152:153] op_sel_hi:[1,0]
	v_mul_f32_e32 v128, 0xbfb8aa3b, v126
	v_mul_f32_e32 v129, 0xbfb8aa3b, v127
	v_exp_f32_e32 v128, v128
	v_exp_f32_e32 v129, v129
	v_pk_mul_f32 v[102:103], v[102:103], v[152:153] op_sel_hi:[1,0]
	v_pk_mul_f32 v[98:99], v[98:99], v[152:153] op_sel_hi:[1,0]
	v_add_f32_e32 v128, 1.0, v128
	v_add_f32_e32 v129, 1.0, v129
	v_rcp_f32_e32 v128, v128
	v_rcp_f32_e32 v129, v129
	v_pk_mul_f32 v[100:101], v[100:101], v[152:153] op_sel_hi:[1,0]
	v_pk_mul_f32 v[94:95], v[94:95], v[150:151] op_sel_hi:[1,0]
	v_pk_mul_f32 v[90:91], v[90:91], v[150:151] op_sel_hi:[1,0]
	v_pk_mul_f32 v[126:127], v[126:127], v[128:129]
	v_pk_mul_f32 v[92:93], v[92:93], v[150:151] op_sel_hi:[1,0]
	v_pk_mul_f32 v[120:121], v[120:121], v[126:127]
	v_mul_f32_e32 v126, 0xbfb8aa3b, v122
	v_mul_f32_e32 v127, 0xbfb8aa3b, v123
	v_exp_f32_e32 v126, v126
	v_exp_f32_e32 v127, v127
	v_pk_mul_f32 v[86:87], v[86:87], v[150:151] op_sel_hi:[1,0]
	v_pk_mul_f32 v[82:83], v[82:83], v[150:151] op_sel_hi:[1,0]
	v_add_f32_e32 v126, 1.0, v126
	v_add_f32_e32 v127, 1.0, v127
	v_rcp_f32_e32 v126, v126
	v_rcp_f32_e32 v127, v127
	v_pk_mul_f32 v[84:85], v[84:85], v[150:151] op_sel_hi:[1,0]
	s_waitcnt lgkmcnt(1)
; __device__ __forceinline__ unsigned pk2(float lo, float hi) { f32x2 v = {lo, hi}; bf16x2_t b = __builtin_convertvector(v, bf16x2_t); return __builtin_bit_cast(unsigned, b); }
;     __device__ __forceinline__ void operator()(const AccT& acc, const Unit& u, int wr, int wc, int fr, int fq) const {
;     ...
;         for (int ai = 0; ai < 2; ++ai)
; #pragma unroll
;             for (int m = 0; m < 4; ++m) {
;                 const int row = row0 + ai * HALF + m * 16;
;                 const float rs = rsv[ai * 4 + m];
;                 float v[8];
; #pragma unroll
;                 for (int n = 0; n < 2; ++n)
; #pragma unroll
;                     for (int j = 0; j < 4; ++j) {
;                         const float g = acc[ai][0][m][n][j] * rs, up = acc[ai][1][m][n][j] * rs;
;                         const float sg = __builtin_amdgcn_rcpf(1.0f + __builtin_amdgcn_exp2f(-g * LOG2E));
;                         v[4 * n + j] = g * sg * up;
;                     }
;                 u32x4 w; w.x = pk2(v[0], v[1]); w.y = pk2(v[2], v[3]); w.z = pk2(v[4], v[5]); w.w = pk2(v[6], v[7]);
;                 *(u32x4*)(mid + (size_t)row * FF + col0) = w;
	v_pk_mul_f32 v[78:79], v[78:79], v[148:149] op_sel_hi:[1,0]
	v_pk_mul_f32 v[74:75], v[74:75], v[148:149] op_sel_hi:[1,0]
	v_pk_mul_f32 v[122:123], v[122:123], v[126:127]
	v_pk_mul_f32 v[76:77], v[76:77], v[148:149] op_sel_hi:[1,0]
	v_pk_mul_f32 v[122:123], v[114:115], v[122:123]
	v_pk_mul_f32 v[114:115], v[124:125], v[156:157] op_sel_hi:[1,0]
	v_pk_mul_f32 v[70:71], v[70:71], v[148:149] op_sel_hi:[1,0]
	v_mul_f32_e32 v124, 0xbfb8aa3b, v114
	v_mul_f32_e32 v125, 0xbfb8aa3b, v115
	v_exp_f32_e32 v124, v124
	v_exp_f32_e32 v125, v125
	v_pk_mul_f32 v[66:67], v[66:67], v[148:149] op_sel_hi:[1,0]
	v_pk_mul_f32 v[68:69], v[68:69], v[148:149] op_sel_hi:[1,0]
	v_add_f32_e32 v124, 1.0, v124
	v_add_f32_e32 v125, 1.0, v125
	v_rcp_f32_e32 v124, v124
	v_rcp_f32_e32 v125, v125
	v_pk_mul_f32 v[62:63], v[62:63], v[146:147] op_sel_hi:[1,0]
	v_pk_mul_f32 v[58:59], v[58:59], v[146:147] op_sel_hi:[1,0]
	v_pk_mul_f32 v[60:61], v[60:61], v[146:147] op_sel_hi:[1,0]
	v_pk_mul_f32 v[114:115], v[114:115], v[124:125]
	v_pk_mul_f32 v[54:55], v[54:55], v[146:147] op_sel_hi:[1,0]
	v_pk_mul_f32 v[124:125], v[116:117], v[114:115]
	v_cvt_pk_bf16_f32 v114, v118, v119
	v_mov_b64_e32 v[118:119], s[46:47]
	v_cvt_pk_bf16_f32 v115, v120, v121
	v_cvt_pk_bf16_f32 v116, v122, v123
	v_mad_i64_i32 v[122:123], s[46:47], v153, s39, v[118:119]
	v_lshlrev_b64 v[120:121], 1, v[154:155]
	v_cvt_pk_bf16_f32 v117, v124, v125
	v_lshl_add_u64 v[122:123], v[122:123], 0, v[120:121]
	global_store_dwordx4 v[122:123], v[114:117], off
	v_pk_mul_f32 v[50:51], v[50:51], v[146:147] op_sel_hi:[1,0]
	v_pk_mul_f32 v[52:53], v[52:53], v[146:147] op_sel_hi:[1,0]
	v_mul_f32_e32 v114, 0xbfb8aa3b, v110
	v_mul_f32_e32 v115, 0xbfb8aa3b, v111
	v_exp_f32_e32 v114, v114
	v_exp_f32_e32 v115, v115
	v_pk_mul_f32 v[46:47], v[46:47], v[144:145] op_sel_hi:[1,0]
	v_pk_mul_f32 v[42:43], v[42:43], v[144:145] op_sel_hi:[1,0]
	v_add_f32_e32 v114, 1.0, v114
	v_add_f32_e32 v115, 1.0, v115
	v_rcp_f32_e32 v114, v114
	v_rcp_f32_e32 v115, v115
	v_pk_mul_f32 v[44:45], v[44:45], v[144:145] op_sel_hi:[1,0]
	v_pk_mul_f32 v[38:39], v[38:39], v[144:145] op_sel_hi:[1,0]
	v_pk_mul_f32 v[34:35], v[34:35], v[144:145] op_sel_hi:[1,0]
	v_pk_mul_f32 v[110:111], v[110:111], v[114:115]
	v_pk_mul_f32 v[36:37], v[36:37], v[144:145] op_sel_hi:[1,0]
	v_pk_mul_f32 v[106:107], v[106:107], v[110:111]
	v_pk_mul_f32 v[110:111], v[112:113], v[152:153] op_sel_hi:[1,0]
	v_pk_mul_f32 v[30:31], v[30:31], v[142:143] op_sel_hi:[1,0]
	v_mul_f32_e32 v112, 0xbfb8aa3b, v110
	v_mul_f32_e32 v113, 0xbfb8aa3b, v111
	v_exp_f32_e32 v112, v112
	v_exp_f32_e32 v113, v113
	v_pk_mul_f32 v[26:27], v[26:27], v[142:143] op_sel_hi:[1,0]
	v_pk_mul_f32 v[28:29], v[28:29], v[142:143] op_sel_hi:[1,0]
	v_add_f32_e32 v112, 1.0, v112
	v_add_f32_e32 v113, 1.0, v113
	v_rcp_f32_e32 v112, v112
	v_rcp_f32_e32 v113, v113
	v_pk_mul_f32 v[22:23], v[22:23], v[142:143] op_sel_hi:[1,0]
	v_pk_mul_f32 v[18:19], v[18:19], v[142:143] op_sel_hi:[1,0]
	v_pk_mul_f32 v[20:21], v[20:21], v[142:143] op_sel_hi:[1,0]
	v_pk_mul_f32 v[110:111], v[110:111], v[112:113]
	s_waitcnt lgkmcnt(0)
	v_pk_mul_f32 v[14:15], v[14:15], v[140:141] op_sel_hi:[1,0]
	v_pk_mul_f32 v[108:109], v[108:109], v[110:111]
	v_mul_f32_e32 v110, 0xbfb8aa3b, v102
	v_mul_f32_e32 v111, 0xbfb8aa3b, v103
	v_exp_f32_e32 v110, v110
	v_exp_f32_e32 v111, v111
	v_pk_mul_f32 v[10:11], v[10:11], v[140:141] op_sel_hi:[1,0]
	v_pk_mul_f32 v[12:13], v[12:13], v[140:141] op_sel_hi:[1,0]
	v_add_f32_e32 v110, 1.0, v110
	v_add_f32_e32 v111, 1.0, v111
	v_rcp_f32_e32 v110, v110
	v_rcp_f32_e32 v111, v111
	v_pk_mul_f32 v[6:7], v[6:7], v[140:141] op_sel_hi:[1,0]
	v_pk_mul_f32 v[2:3], v[2:3], v[140:141] op_sel_hi:[1,0]
	v_pk_mul_f32 v[4:5], v[4:5], v[140:141] op_sel_hi:[1,0]
	v_pk_mul_f32 v[102:103], v[102:103], v[110:111]
	v_or_b32_e32 v110, 16, v153
	v_pk_mul_f32 v[102:103], v[98:99], v[102:103]
	v_pk_mul_f32 v[98:99], v[104:105], v[152:153] op_sel_hi:[1,0]
	s_mov_b32 s65, s38
	v_mul_f32_e32 v104, 0xbfb8aa3b, v98
	v_mul_f32_e32 v105, 0xbfb8aa3b, v99
	v_exp_f32_e32 v104, v104
	v_exp_f32_e32 v105, v105
	v_add_f32_e32 v104, 1.0, v104
	v_add_f32_e32 v105, 1.0, v105
	v_rcp_f32_e32 v104, v104
	v_rcp_f32_e32 v105, v105
	s_nop 0
	v_pk_mul_f32 v[98:99], v[98:99], v[104:105]
	s_nop 0
	v_pk_mul_f32 v[104:105], v[100:101], v[98:99]
	v_cvt_pk_bf16_f32 v100, v102, v103
	v_mad_i64_i32 v[102:103], s[46:47], v110, s39, v[118:119]
	v_cvt_pk_bf16_f32 v98, v106, v107
	v_cvt_pk_bf16_f32 v99, v108, v109
	v_cvt_pk_bf16_f32 v101, v104, v105
	v_lshl_add_u64 v[102:103], v[102:103], 0, v[120:121]
	global_store_dwordx4 v[102:103], v[98:101], off
	s_nop 1
	v_mul_f32_e32 v98, 0xbfb8aa3b, v94
	v_mul_f32_e32 v99, 0xbfb8aa3b, v95
	v_exp_f32_e32 v98, v98
	v_exp_f32_e32 v99, v99
	v_add_f32_e32 v98, 1.0, v98
	v_add_f32_e32 v99, 1.0, v99
	v_rcp_f32_e32 v98, v98
	v_rcp_f32_e32 v99, v99
	s_nop 0
	v_pk_mul_f32 v[94:95], v[94:95], v[98:99]
	s_nop 0
	v_pk_mul_f32 v[90:91], v[90:91], v[94:95]
	v_pk_mul_f32 v[94:95], v[96:97], v[150:151] op_sel_hi:[1,0]
	s_nop 0
	v_mul_f32_e32 v96, 0xbfb8aa3b, v94
	v_mul_f32_e32 v97, 0xbfb8aa3b, v95
	v_exp_f32_e32 v96, v96
	v_exp_f32_e32 v97, v97
	v_add_f32_e32 v96, 1.0, v96
	v_add_f32_e32 v97, 1.0, v97
	v_rcp_f32_e32 v96, v96
	v_rcp_f32_e32 v97, v97
	s_nop 0
	v_pk_mul_f32 v[94:95], v[94:95], v[96:97]
	s_nop 0
	v_pk_mul_f32 v[92:93], v[92:93], v[94:95]
	v_mul_f32_e32 v94, 0xbfb8aa3b, v86
	v_mul_f32_e32 v95, 0xbfb8aa3b, v87
	v_exp_f32_e32 v94, v94
	v_exp_f32_e32 v95, v95
	v_add_f32_e32 v94, 1.0, v94
	v_add_f32_e32 v95, 1.0, v95
	v_rcp_f32_e32 v94, v94
	v_rcp_f32_e32 v95, v95
	s_nop 0
	v_pk_mul_f32 v[86:87], v[86:87], v[94:95]
	s_nop 0
	v_pk_mul_f32 v[86:87], v[82:83], v[86:87]
; __device__ __forceinline__ unsigned pk2(float lo, float hi) { f32x2 v = {lo, hi}; bf16x2_t b = __builtin_convertvector(v, bf16x2_t); return __builtin_bit_cast(unsigned, b); }
;     __device__ __forceinline__ void operator()(const AccT& acc, const Unit& u, int wr, int wc, int fr, int fq) const {
;     ...
; #pragma unroll
;         for (int ai = 0; ai < 2; ++ai)
; #pragma unroll
;             for (int m = 0; m < 4; ++m) {
;                 const int row = row0 + ai * HALF + m * 16;
;                 const float rs = rsv[ai * 4 + m];
;                 float v[8];
; #pragma unroll
;                 for (int n = 0; n < 2; ++n)
; #pragma unroll
;                     for (int j = 0; j < 4; ++j) {
;                         const float g = acc[ai][0][m][n][j] * rs, up = acc[ai][1][m][n][j] * rs;
;                         const float sg = __builtin_amdgcn_rcpf(1.0f + __builtin_amdgcn_exp2f(-g * LOG2E));
;                         v[4 * n + j] = g * sg * up;
;                     }
;                 u32x4 w; w.x = pk2(v[0], v[1]); w.y = pk2(v[2], v[3]); w.z = pk2(v[4], v[5]); w.w = pk2(v[6], v[7]);
;                 *(u32x4*)(mid + (size_t)row * FF + col0) = w;
;             }
	v_pk_mul_f32 v[82:83], v[88:89], v[150:151] op_sel_hi:[1,0]
	v_or_b32_e32 v94, 32, v153
	v_mul_f32_e32 v88, 0xbfb8aa3b, v82
	v_mul_f32_e32 v89, 0xbfb8aa3b, v83
	v_exp_f32_e32 v88, v88
	v_exp_f32_e32 v89, v89
	v_add_f32_e32 v88, 1.0, v88
	v_add_f32_e32 v89, 1.0, v89
	v_rcp_f32_e32 v88, v88
	v_rcp_f32_e32 v89, v89
	s_nop 0
	v_pk_mul_f32 v[82:83], v[82:83], v[88:89]
	s_nop 0
	v_pk_mul_f32 v[88:89], v[84:85], v[82:83]
	v_cvt_pk_bf16_f32 v84, v86, v87
	v_mad_i64_i32 v[86:87], s[46:47], v94, s39, v[118:119]
	v_cvt_pk_bf16_f32 v82, v90, v91
	v_cvt_pk_bf16_f32 v83, v92, v93
	v_cvt_pk_bf16_f32 v85, v88, v89
	v_lshl_add_u64 v[86:87], v[86:87], 0, v[120:121]
	global_store_dwordx4 v[86:87], v[82:85], off
	s_nop 1
	v_mul_f32_e32 v82, 0xbfb8aa3b, v78
	v_mul_f32_e32 v83, 0xbfb8aa3b, v79
	v_exp_f32_e32 v82, v82
	v_exp_f32_e32 v83, v83
	v_add_f32_e32 v82, 1.0, v82
	v_add_f32_e32 v83, 1.0, v83
	v_rcp_f32_e32 v82, v82
	v_rcp_f32_e32 v83, v83
	s_nop 0
	v_pk_mul_f32 v[78:79], v[78:79], v[82:83]
	s_nop 0
	v_pk_mul_f32 v[74:75], v[74:75], v[78:79]
	v_pk_mul_f32 v[78:79], v[80:81], v[148:149] op_sel_hi:[1,0]
	s_nop 0
	v_mul_f32_e32 v80, 0xbfb8aa3b, v78
	v_mul_f32_e32 v81, 0xbfb8aa3b, v79
	v_exp_f32_e32 v80, v80
	v_exp_f32_e32 v81, v81
	v_add_f32_e32 v80, 1.0, v80
	v_add_f32_e32 v81, 1.0, v81
	v_rcp_f32_e32 v80, v80
	v_rcp_f32_e32 v81, v81
	s_nop 0
	v_pk_mul_f32 v[78:79], v[78:79], v[80:81]
	s_nop 0
	v_pk_mul_f32 v[76:77], v[76:77], v[78:79]
	v_mul_f32_e32 v78, 0xbfb8aa3b, v70
	v_mul_f32_e32 v79, 0xbfb8aa3b, v71
	v_exp_f32_e32 v78, v78
	v_exp_f32_e32 v79, v79
	v_add_f32_e32 v78, 1.0, v78
	v_add_f32_e32 v79, 1.0, v79
	v_rcp_f32_e32 v78, v78
	v_rcp_f32_e32 v79, v79
	s_nop 0
	v_pk_mul_f32 v[70:71], v[70:71], v[78:79]
	s_nop 0
	v_pk_mul_f32 v[70:71], v[66:67], v[70:71]
	v_pk_mul_f32 v[66:67], v[72:73], v[148:149] op_sel_hi:[1,0]
	v_or_b32_e32 v78, 48, v153
	v_mul_f32_e32 v72, 0xbfb8aa3b, v66
	v_mul_f32_e32 v73, 0xbfb8aa3b, v67
	v_exp_f32_e32 v72, v72
	v_exp_f32_e32 v73, v73
	v_add_f32_e32 v72, 1.0, v72
	v_add_f32_e32 v73, 1.0, v73
	v_rcp_f32_e32 v72, v72
	v_rcp_f32_e32 v73, v73
	s_nop 0
	v_pk_mul_f32 v[66:67], v[66:67], v[72:73]
	s_nop 0
	v_pk_mul_f32 v[72:73], v[68:69], v[66:67]
	v_cvt_pk_bf16_f32 v68, v70, v71
	v_mad_i64_i32 v[70:71], s[46:47], v78, s39, v[118:119]
	v_cvt_pk_bf16_f32 v66, v74, v75
	v_cvt_pk_bf16_f32 v67, v76, v77
	v_cvt_pk_bf16_f32 v69, v72, v73
	v_lshl_add_u64 v[70:71], v[70:71], 0, v[120:121]
	global_store_dwordx4 v[70:71], v[66:69], off
	s_nop 1
	v_mul_f32_e32 v66, 0xbfb8aa3b, v62
	v_mul_f32_e32 v67, 0xbfb8aa3b, v63
	v_exp_f32_e32 v66, v66
	v_exp_f32_e32 v67, v67
	v_add_u32_e32 v68, 0x80, v153
	v_add_f32_e32 v66, 1.0, v66
	v_add_f32_e32 v67, 1.0, v67
	v_rcp_f32_e32 v66, v66
	v_rcp_f32_e32 v67, v67
	s_nop 0
	v_pk_mul_f32 v[62:63], v[62:63], v[66:67]
	s_nop 0
	v_pk_mul_f32 v[58:59], v[58:59], v[62:63]
	v_pk_mul_f32 v[62:63], v[64:65], v[146:147] op_sel_hi:[1,0]
	s_nop 0
	v_mul_f32_e32 v64, 0xbfb8aa3b, v62
	v_mul_f32_e32 v65, 0xbfb8aa3b, v63
	v_exp_f32_e32 v64, v64
	v_exp_f32_e32 v65, v65
	v_add_f32_e32 v64, 1.0, v64
	v_add_f32_e32 v65, 1.0, v65
	v_rcp_f32_e32 v64, v64
	v_rcp_f32_e32 v65, v65
	s_nop 0
	v_pk_mul_f32 v[62:63], v[62:63], v[64:65]
	s_nop 0
	v_pk_mul_f32 v[60:61], v[60:61], v[62:63]
	v_mul_f32_e32 v62, 0xbfb8aa3b, v54
	v_mul_f32_e32 v63, 0xbfb8aa3b, v55
	v_exp_f32_e32 v62, v62
	v_exp_f32_e32 v63, v63
	v_add_f32_e32 v62, 1.0, v62
	v_add_f32_e32 v63, 1.0, v63
	v_rcp_f32_e32 v62, v62
	v_rcp_f32_e32 v63, v63
	s_nop 0
	v_pk_mul_f32 v[54:55], v[54:55], v[62:63]
	s_nop 0
	v_pk_mul_f32 v[54:55], v[50:51], v[54:55]
	v_pk_mul_f32 v[50:51], v[56:57], v[146:147] op_sel_hi:[1,0]
	s_nop 0
	v_mul_f32_e32 v56, 0xbfb8aa3b, v50
	v_mul_f32_e32 v57, 0xbfb8aa3b, v51
	v_exp_f32_e32 v56, v56
	v_exp_f32_e32 v57, v57
	v_add_f32_e32 v56, 1.0, v56
	v_add_f32_e32 v57, 1.0, v57
	v_rcp_f32_e32 v56, v56
	v_rcp_f32_e32 v57, v57
	s_nop 0
	v_pk_mul_f32 v[50:51], v[50:51], v[56:57]
	s_nop 0
	v_pk_mul_f32 v[56:57], v[52:53], v[50:51]
	v_cvt_pk_bf16_f32 v52, v54, v55
	v_mad_i64_i32 v[54:55], s[46:47], v68, s39, v[118:119]
	v_cvt_pk_bf16_f32 v50, v58, v59
	v_cvt_pk_bf16_f32 v51, v60, v61
	v_cvt_pk_bf16_f32 v53, v56, v57
	v_lshl_add_u64 v[54:55], v[54:55], 0, v[120:121]
	global_store_dwordx4 v[54:55], v[50:53], off
	s_nop 1
	v_mul_f32_e32 v50, 0xbfb8aa3b, v46
	v_mul_f32_e32 v51, 0xbfb8aa3b, v47
	v_exp_f32_e32 v50, v50
	v_exp_f32_e32 v51, v51
	v_add_f32_e32 v50, 1.0, v50
	v_add_f32_e32 v51, 1.0, v51
	v_rcp_f32_e32 v50, v50
	v_rcp_f32_e32 v51, v51
	s_nop 0
	v_pk_mul_f32 v[46:47], v[46:47], v[50:51]
	s_nop 0
	v_pk_mul_f32 v[42:43], v[42:43], v[46:47]
	v_pk_mul_f32 v[46:47], v[48:49], v[144:145] op_sel_hi:[1,0]
	s_nop 0
	v_mul_f32_e32 v48, 0xbfb8aa3b, v46
	v_mul_f32_e32 v49, 0xbfb8aa3b, v47
	v_exp_f32_e32 v48, v48
	v_exp_f32_e32 v49, v49
	v_add_f32_e32 v48, 1.0, v48
; __device__ __forceinline__ unsigned pk2(float lo, float hi) { f32x2 v = {lo, hi}; bf16x2_t b = __builtin_convertvector(v, bf16x2_t); return __builtin_bit_cast(unsigned, b); }
; #define PG8_WAIT_V(n) asm volatile("s_waitcnt vmcnt(" #n ")" ::: "memory")
; #define PG8_BAR __builtin_amdgcn_s_barrier()
;     __device__ __forceinline__ void operator()(const AccT& acc, const Unit& u, int wr, int wc, int fr, int fq) const {
;     ...
; #pragma unroll
;         for (int ai = 0; ai < 2; ++ai)
; #pragma unroll
;             for (int m = 0; m < 4; ++m) {
;                 const int row = row0 + ai * HALF + m * 16;
;                 const float rs = rsv[ai * 4 + m];
;                 float v[8];
; #pragma unroll
;                 for (int n = 0; n < 2; ++n)
; #pragma unroll
;                     for (int j = 0; j < 4; ++j) {
;                         const float g = acc[ai][0][m][n][j] * rs, up = acc[ai][1][m][n][j] * rs;
;                         const float sg = __builtin_amdgcn_rcpf(1.0f + __builtin_amdgcn_exp2f(-g * LOG2E));
;                         v[4 * n + j] = g * sg * up;
;                     }
;                 u32x4 w; w.x = pk2(v[0], v[1]); w.y = pk2(v[2], v[3]); w.z = pk2(v[4], v[5]); w.w = pk2(v[6], v[7]);
;                 *(u32x4*)(mid + (size_t)row * FF + col0) = w;
;             }
; template <class Epi>
; __device__ __forceinline__ void gemm_phase(LAS unsigned char* lds, const Gemm g, const StaticOrder& S, const Epi& E) {
;     ...
;         E(acc, cur, wr, wc, fr, fq);
;         if (!has_next) break;
; #pragma unroll
;         for (int a = 0; a < 2; ++a)
; #pragma unroll
;             for (int b = 0; b < 2; ++b)
; #pragma unroll
;                 for (int m = 0; m < 4; ++m)
; #pragma unroll
;                     for (int n = 0; n < 2; ++n) acc[a][b][m][n] = (f32x4){0.f, 0.f, 0.f, 0.f};
;         cur = nxt; cA = nA; cB = nB; ++ui;
;     }
;     PG8_WAIT_V(0);
;     if (wr == 0) PG8_BAR;
;     PG8_BAR;
	v_add_f32_e32 v49, 1.0, v49
	v_rcp_f32_e32 v48, v48
	v_rcp_f32_e32 v49, v49
	s_nop 0
	v_pk_mul_f32 v[46:47], v[46:47], v[48:49]
	s_nop 0
	v_pk_mul_f32 v[44:45], v[44:45], v[46:47]
	v_mul_f32_e32 v46, 0xbfb8aa3b, v38
	v_mul_f32_e32 v47, 0xbfb8aa3b, v39
	v_exp_f32_e32 v46, v46
	v_exp_f32_e32 v47, v47
	v_add_f32_e32 v46, 1.0, v46
	v_add_f32_e32 v47, 1.0, v47
	v_rcp_f32_e32 v46, v46
	v_rcp_f32_e32 v47, v47
	s_nop 0
	v_pk_mul_f32 v[38:39], v[38:39], v[46:47]
	s_nop 0
	v_pk_mul_f32 v[38:39], v[34:35], v[38:39]
	v_pk_mul_f32 v[34:35], v[40:41], v[144:145] op_sel_hi:[1,0]
	v_add_u32_e32 v46, 0x90, v153
	v_mul_f32_e32 v40, 0xbfb8aa3b, v34
	v_mul_f32_e32 v41, 0xbfb8aa3b, v35
	v_exp_f32_e32 v40, v40
	v_exp_f32_e32 v41, v41
	v_add_f32_e32 v40, 1.0, v40
	v_add_f32_e32 v41, 1.0, v41
	v_rcp_f32_e32 v40, v40
	v_rcp_f32_e32 v41, v41
	s_nop 0
	v_pk_mul_f32 v[34:35], v[34:35], v[40:41]
	s_nop 0
	v_pk_mul_f32 v[40:41], v[36:37], v[34:35]
	v_cvt_pk_bf16_f32 v36, v38, v39
	v_mad_i64_i32 v[38:39], s[46:47], v46, s39, v[118:119]
	v_cvt_pk_bf16_f32 v34, v42, v43
	v_cvt_pk_bf16_f32 v35, v44, v45
	v_cvt_pk_bf16_f32 v37, v40, v41
	v_lshl_add_u64 v[38:39], v[38:39], 0, v[120:121]
	global_store_dwordx4 v[38:39], v[34:37], off
	s_nop 1
	v_mul_f32_e32 v34, 0xbfb8aa3b, v30
	v_mul_f32_e32 v35, 0xbfb8aa3b, v31
	v_exp_f32_e32 v34, v34
	v_exp_f32_e32 v35, v35
	v_add_f32_e32 v34, 1.0, v34
	v_add_f32_e32 v35, 1.0, v35
	v_rcp_f32_e32 v34, v34
	v_rcp_f32_e32 v35, v35
	s_nop 0
	v_pk_mul_f32 v[30:31], v[30:31], v[34:35]
	s_nop 0
	v_pk_mul_f32 v[26:27], v[26:27], v[30:31]
	v_pk_mul_f32 v[30:31], v[32:33], v[142:143] op_sel_hi:[1,0]
	s_nop 0
	v_mul_f32_e32 v32, 0xbfb8aa3b, v30
	v_mul_f32_e32 v33, 0xbfb8aa3b, v31
	v_exp_f32_e32 v32, v32
	v_exp_f32_e32 v33, v33
	v_add_f32_e32 v32, 1.0, v32
	v_add_f32_e32 v33, 1.0, v33
	v_rcp_f32_e32 v32, v32
	v_rcp_f32_e32 v33, v33
	s_nop 0
	v_pk_mul_f32 v[30:31], v[30:31], v[32:33]
	s_nop 0
	v_pk_mul_f32 v[28:29], v[28:29], v[30:31]
	v_mul_f32_e32 v30, 0xbfb8aa3b, v22
	v_mul_f32_e32 v31, 0xbfb8aa3b, v23
	v_exp_f32_e32 v30, v30
	v_exp_f32_e32 v31, v31
	v_add_f32_e32 v30, 1.0, v30
	v_add_f32_e32 v31, 1.0, v31
	v_rcp_f32_e32 v30, v30
	v_rcp_f32_e32 v31, v31
	s_nop 0
	v_pk_mul_f32 v[22:23], v[22:23], v[30:31]
	s_nop 0
	v_pk_mul_f32 v[22:23], v[18:19], v[22:23]
	v_pk_mul_f32 v[18:19], v[24:25], v[142:143] op_sel_hi:[1,0]
	v_add_u32_e32 v30, 0xa0, v153
	v_mul_f32_e32 v24, 0xbfb8aa3b, v18
	v_mul_f32_e32 v25, 0xbfb8aa3b, v19
	v_exp_f32_e32 v24, v24
	v_exp_f32_e32 v25, v25
	v_add_f32_e32 v24, 1.0, v24
	v_add_f32_e32 v25, 1.0, v25
	v_rcp_f32_e32 v24, v24
	v_rcp_f32_e32 v25, v25
	s_nop 0
	v_pk_mul_f32 v[18:19], v[18:19], v[24:25]
	s_nop 0
	v_pk_mul_f32 v[24:25], v[20:21], v[18:19]
	v_cvt_pk_bf16_f32 v20, v22, v23
	v_mad_i64_i32 v[22:23], s[46:47], v30, s39, v[118:119]
	v_cvt_pk_bf16_f32 v18, v26, v27
	v_cvt_pk_bf16_f32 v19, v28, v29
	v_cvt_pk_bf16_f32 v21, v24, v25
	v_lshl_add_u64 v[22:23], v[22:23], 0, v[120:121]
	global_store_dwordx4 v[22:23], v[18:21], off
	s_nop 1
	v_mul_f32_e32 v18, 0xbfb8aa3b, v14
	v_mul_f32_e32 v19, 0xbfb8aa3b, v15
	v_exp_f32_e32 v18, v18
	v_exp_f32_e32 v19, v19
	v_add_f32_e32 v18, 1.0, v18
	v_add_f32_e32 v19, 1.0, v19
	v_rcp_f32_e32 v18, v18
	v_rcp_f32_e32 v19, v19
	s_nop 0
	v_pk_mul_f32 v[14:15], v[14:15], v[18:19]
	s_nop 0
	v_pk_mul_f32 v[10:11], v[10:11], v[14:15]
	v_pk_mul_f32 v[14:15], v[16:17], v[140:141] op_sel_hi:[1,0]
	s_nop 0
	v_mul_f32_e32 v16, 0xbfb8aa3b, v14
	v_mul_f32_e32 v17, 0xbfb8aa3b, v15
	v_exp_f32_e32 v16, v16
	v_exp_f32_e32 v17, v17
	v_add_f32_e32 v16, 1.0, v16
	v_add_f32_e32 v17, 1.0, v17
	v_rcp_f32_e32 v16, v16
	v_rcp_f32_e32 v17, v17
	s_nop 0
	v_pk_mul_f32 v[14:15], v[14:15], v[16:17]
	s_nop 0
	v_pk_mul_f32 v[12:13], v[12:13], v[14:15]
	v_mul_f32_e32 v14, 0xbfb8aa3b, v6
	v_mul_f32_e32 v15, 0xbfb8aa3b, v7
	v_exp_f32_e32 v14, v14
	v_exp_f32_e32 v15, v15
	v_add_f32_e32 v14, 1.0, v14
	v_add_f32_e32 v15, 1.0, v15
	v_rcp_f32_e32 v14, v14
	v_rcp_f32_e32 v15, v15
	s_nop 0
	v_pk_mul_f32 v[6:7], v[6:7], v[14:15]
	s_nop 0
	v_pk_mul_f32 v[6:7], v[2:3], v[6:7]
	v_pk_mul_f32 v[2:3], v[8:9], v[140:141] op_sel_hi:[1,0]
	v_add_u32_e32 v14, 0xb0, v153
	v_mul_f32_e32 v8, 0xbfb8aa3b, v2
	v_mul_f32_e32 v9, 0xbfb8aa3b, v3
	v_exp_f32_e32 v8, v8
	v_exp_f32_e32 v9, v9
	v_add_f32_e32 v8, 1.0, v8
	v_add_f32_e32 v9, 1.0, v9
	v_rcp_f32_e32 v8, v8
	v_rcp_f32_e32 v9, v9
	s_nop 0
	v_pk_mul_f32 v[2:3], v[2:3], v[8:9]
	s_nop 0
	v_pk_mul_f32 v[8:9], v[4:5], v[2:3]
	v_cvt_pk_bf16_f32 v4, v6, v7
	v_mad_i64_i32 v[6:7], s[46:47], v14, s39, v[118:119]
	v_cvt_pk_bf16_f32 v2, v10, v11
	v_cvt_pk_bf16_f32 v3, v12, v13
	v_cvt_pk_bf16_f32 v5, v8, v9
	v_lshl_add_u64 v[6:7], v[6:7], 0, v[120:121]
	s_mov_b64 s[46:47], s[42:43]
	global_store_dwordx4 v[6:7], v[2:5], off
	s_cbranch_vccz .LBB0_87
	s_waitcnt vmcnt(0)
	s_cmpk_gt_u32 s52, 0xff
	s_cbranch_scc1 .LBB0_94
	s_barrier

; #define PG8_STAGE(bufoff, gbase, voff) do { _Pragma("unroll") for (int _i = 0; _i < 2; ++_i) \
;         __builtin_amdgcn_global_load_lds((const unsigned*)((const char*)(gbase) + (voff)[_i]), (LAS unsigned*)(lds + (bufoff) + ldsw + _i * 8192), 16, 0, 0); } while (0)
; #define PG8_LDA(dst, b, h) do { _Pragma("unroll") for (int m = 0; m < 4; ++m) _Pragma("unroll") for (int k = 0; k < 2; ++k) dst[m][k] = *(const LAS bf16x8*)(lds + PG8_SA(b, h) + aoff + m * 2048 + k * 1024); } while (0)
; #define PG8_LDB(dst, b, h) do { _Pragma("unroll") for (int n = 0; n < 2; ++n) _Pragma("unroll") for (int k = 0; k < 2; ++k) dst[n][k] = *(const LAS bf16x8*)(lds + PG8_SB(b, h) + boff + n * 2048 + k * 1024); } while (0)
; #define PG8_MMA(ai, bj, At, Bt) do { __builtin_amdgcn_s_setprio(1); _Pragma("unroll") for (int m = 0; m < 4; ++m) _Pragma("unroll") for (int n = 0; n < 2; ++n) _Pragma("unroll") for (int k = 0; k < 2; ++k) \
;         acc[ai][bj][m][n] = __builtin_amdgcn_mfma_f32_16x16x32_bf16(Bt[n][k], At[m][k], acc[ai][bj][m][n], 0, 0, 0); __builtin_amdgcn_s_setprio(0); } while (0)
; #define PG8_WAIT_V(n) asm volatile("s_waitcnt vmcnt(" #n ")" ::: "memory")
; #define PG8_WAIT_L(n) asm volatile("s_waitcnt lgkmcnt(" #n ")" ::: "memory")
; #define PG8_BAR __builtin_amdgcn_s_barrier()
; #define PG8_SCHED __builtin_amdgcn_sched_barrier(0)
; template <class Epi>
; __device__ __forceinline__ void gemm_phase(LAS unsigned char* lds, const Gemm g, const StaticOrder& S, const Epi& E) {
;     ...
;             PG8_LDB(B0, 0, 0); PG8_SCHED; PG8_LDA(At, 0, 0); PG8_STAGE(PG8_SA(1, 1), a1 + hstep, voffA);
;             PG8_WAIT_L(8); PG8_BAR; PG8_WAIT_L(0); PG8_MMA(0, 0, At, B0); PG8_BAR; PG8_SCHED;
;             PG8_LDB(B1, 0, 1); PG8_STAGE(PG8_SB(0, 0), b2, voffB);
;             PG8_BAR; PG8_WAIT_L(0); PG8_MMA(0, 1, At, B1); PG8_BAR;
;             PG8_LDA(At, 0, 1); PG8_STAGE(PG8_SA(0, 0), a2, voffA);
;             PG8_BAR; PG8_WAIT_L(0); PG8_MMA(1, 0, At, B0); PG8_BAR; PG8_SCHED;
;             PG8_STAGE(PG8_SB(0, 1), b2 + hstep, voffB);
;             PG8_WAIT_V(6); PG8_BAR; PG8_MMA(1, 1, At, B1); PG8_BAR;
;             PG8_LDB(B0, 1, 0); PG8_SCHED; PG8_LDA(At, 1, 0); PG8_STAGE(PG8_SA(0, 1), a2 + hstep, voffA);
.LBB0_654:
	s_add_i32 s84, s62, 2
	s_add_u32 s64, s60, 0x80
	s_addc_u32 s63, s61, 0
	s_add_i32 s85, 0, 0x10000
	s_cmp_eq_u32 s77, s62
	s_cselect_b32 s62, s2, s64
	s_cselect_b32 s63, s3, s63
	s_cselect_b32 s65, s41, s83
	s_cselect_b32 s64, s40, s82
	s_add_i32 m0, s70, 0xc000
	ds_read_b128 v[146:149], v243
	ds_read_b128 v[150:153], v243 offset:1024
	ds_read_b128 v[154:157], v243 offset:2048
	ds_read_b128 v[158:161], v243 offset:3072
	ds_read_b128 v[162:165], v243 offset:4096
	ds_read_b128 v[166:169], v243 offset:5120
	ds_read_b128 v[170:173], v243 offset:6144
	ds_read_b128 v[174:177], v243 offset:7168
	global_load_lds_dwordx4 v214, s[60:61]
	s_add_i32 m0, s70, 0xe000
	s_nop 0
	global_load_lds_dwordx4 v216, s[60:61]
	s_waitcnt lgkmcnt(8)
	s_barrier
	s_waitcnt lgkmcnt(0)
	v_mfma_f32_16x16x32_bf16 v[142:145], v[58:61], v[146:149], v[142:145]
	v_mfma_f32_16x16x32_bf16 v[138:141], v[66:69], v[146:149], v[138:141]
	v_mfma_f32_16x16x32_bf16 v[126:129], v[58:61], v[154:157], v[126:129]
	v_mfma_f32_16x16x32_bf16 v[122:125], v[66:69], v[154:157], v[122:125]
	v_mfma_f32_16x16x32_bf16 v[110:113], v[58:61], v[162:165], v[110:113]
	v_mfma_f32_16x16x32_bf16 v[106:109], v[66:69], v[162:165], v[106:109]
	v_mfma_f32_16x16x32_bf16 v[94:97], v[58:61], v[170:173], v[94:97]
	v_mfma_f32_16x16x32_bf16 v[90:93], v[66:69], v[170:173], v[90:93]
	v_mfma_f32_16x16x32_bf16 v[142:145], v[62:65], v[150:153], v[142:145]
	v_mfma_f32_16x16x32_bf16 v[138:141], v[70:73], v[150:153], v[138:141]
	v_mfma_f32_16x16x32_bf16 v[126:129], v[62:65], v[158:161], v[126:129]
	v_mfma_f32_16x16x32_bf16 v[122:125], v[70:73], v[158:161], v[122:125]
	v_mfma_f32_16x16x32_bf16 v[110:113], v[62:65], v[166:169], v[110:113]
	v_mfma_f32_16x16x32_bf16 v[106:109], v[70:73], v[166:169], v[106:109]
	v_mfma_f32_16x16x32_bf16 v[94:97], v[62:65], v[174:177], v[94:97]
	v_mfma_f32_16x16x32_bf16 v[90:93], v[70:73], v[174:177], v[90:93]
	s_barrier
	s_add_i32 s86, 0, 0x14000
	s_add_i32 s85, s85, s69
	s_add_u32 s98, s64, s22
	s_addc_u32 s99, s65, s23
	s_mov_b32 m0, s85
	ds_read_b128 v[178:181], v194 offset:16384
	ds_read_b128 v[182:185], v194 offset:17408
	ds_read_b128 v[186:189], v194 offset:18432
	ds_read_b128 v[190:193], v194 offset:19456
	global_load_lds_dwordx4 v0, s[64:65]
	s_add_i32 m0, s85, 0x2000
	s_nop 0
	global_load_lds_dwordx4 v208, s[64:65]
	s_barrier
	s_waitcnt lgkmcnt(0)
	v_mfma_f32_16x16x32_bf16 v[134:137], v[178:181], v[146:149], v[134:137]
	v_mfma_f32_16x16x32_bf16 v[130:133], v[186:189], v[146:149], v[130:133]
	v_mfma_f32_16x16x32_bf16 v[118:121], v[178:181], v[154:157], v[118:121]
	v_mfma_f32_16x16x32_bf16 v[114:117], v[186:189], v[154:157], v[114:117]
	v_mfma_f32_16x16x32_bf16 v[102:105], v[178:181], v[162:165], v[102:105]
	v_mfma_f32_16x16x32_bf16 v[98:101], v[186:189], v[162:165], v[98:101]
	v_mfma_f32_16x16x32_bf16 v[86:89], v[178:181], v[170:173], v[86:89]
	v_mfma_f32_16x16x32_bf16 v[82:85], v[186:189], v[170:173], v[82:85]
	v_mfma_f32_16x16x32_bf16 v[134:137], v[182:185], v[150:153], v[134:137]
	v_mfma_f32_16x16x32_bf16 v[130:133], v[190:193], v[150:153], v[130:133]
	v_mfma_f32_16x16x32_bf16 v[118:121], v[182:185], v[158:161], v[118:121]
	v_mfma_f32_16x16x32_bf16 v[114:117], v[190:193], v[158:161], v[114:117]
	v_mfma_f32_16x16x32_bf16 v[102:105], v[182:185], v[166:169], v[102:105]
	v_mfma_f32_16x16x32_bf16 v[98:101], v[190:193], v[166:169], v[98:101]
	v_mfma_f32_16x16x32_bf16 v[86:89], v[182:185], v[174:177], v[86:89]
	v_mfma_f32_16x16x32_bf16 v[82:85], v[190:193], v[174:177], v[82:85]
	s_barrier
	ds_read_b128 v[146:149], v243 offset:16384
	ds_read_b128 v[150:153], v243 offset:17408
	ds_read_b128 v[154:157], v243 offset:18432
	ds_read_b128 v[158:161], v243 offset:19456
	ds_read_b128 v[162:165], v243 offset:20480
	ds_read_b128 v[166:169], v243 offset:21504
	ds_read_b128 v[170:173], v243 offset:22528
	s_mov_b32 m0, s70
	s_add_u32 s100, s62, s22
	s_addc_u32 s101, s63, s23
	ds_read_b128 v[174:177], v243 offset:23552
	global_load_lds_dwordx4 v212, s[62:63]
	s_mov_b32 m0, s71
	s_nop 0
	global_load_lds_dwordx4 v210, s[62:63]
	s_waitcnt vmcnt(10)
	s_barrier
	s_waitcnt lgkmcnt(0)
	v_mfma_f32_16x16x32_bf16 v[78:81], v[58:61], v[146:149], v[78:81]
	v_mfma_f32_16x16x32_bf16 v[74:77], v[66:69], v[146:149], v[74:77]
	v_mfma_f32_16x16x32_bf16 v[46:49], v[58:61], v[154:157], v[46:49]
	v_mfma_f32_16x16x32_bf16 v[42:45], v[66:69], v[154:157], v[42:45]
	v_mfma_f32_16x16x32_bf16 v[30:33], v[58:61], v[162:165], v[30:33]
	v_mfma_f32_16x16x32_bf16 v[26:29], v[66:69], v[162:165], v[26:29]
	v_mfma_f32_16x16x32_bf16 v[14:17], v[58:61], v[170:173], v[14:17]
	v_mfma_f32_16x16x32_bf16 v[10:13], v[66:69], v[170:173], v[10:13]
	v_mfma_f32_16x16x32_bf16 v[78:81], v[62:65], v[150:153], v[78:81]
	v_mfma_f32_16x16x32_bf16 v[74:77], v[70:73], v[150:153], v[74:77]
	v_mfma_f32_16x16x32_bf16 v[46:49], v[62:65], v[158:161], v[46:49]
	v_mfma_f32_16x16x32_bf16 v[42:45], v[70:73], v[158:161], v[42:45]
	v_mfma_f32_16x16x32_bf16 v[30:33], v[62:65], v[166:169], v[30:33]
	v_mfma_f32_16x16x32_bf16 v[26:29], v[70:73], v[166:169], v[26:29]
	v_mfma_f32_16x16x32_bf16 v[14:17], v[62:65], v[174:177], v[14:17]
	v_mfma_f32_16x16x32_bf16 v[10:13], v[70:73], v[174:177], v[10:13]
	s_barrier
	ds_read_b128 v[58:61], v194 offset:32768
	ds_read_b128 v[62:65], v194 offset:33792
	ds_read_b128 v[66:69], v194 offset:34816
	ds_read_b128 v[70:73], v194 offset:35840
	s_add_u32 s64, s64, s50
	s_addc_u32 s65, s65, 0
	s_add_i32 s85, s86, s69
	s_mov_b32 m0, s85
	s_add_u32 vcc_lo, s64, s22
	s_addc_u32 vcc_hi, s65, s23
	global_load_lds_dwordx4 v0, s[64:65]
	s_add_i32 m0, s85, 0x2000
	s_nop 0
	global_load_lds_dwordx4 v208, s[64:65]
	s_waitcnt vmcnt(6)
	s_barrier
; #define PG8_STAGE(bufoff, gbase, voff) do { _Pragma("unroll") for (int _i = 0; _i < 2; ++_i) \
;         __builtin_amdgcn_global_load_lds((const unsigned*)((const char*)(gbase) + (voff)[_i]), (LAS unsigned*)(lds + (bufoff) + ldsw + _i * 8192), 16, 0, 0); } while (0)
; #define PG8_LDA(dst, b, h) do { _Pragma("unroll") for (int m = 0; m < 4; ++m) _Pragma("unroll") for (int k = 0; k < 2; ++k) dst[m][k] = *(const LAS bf16x8*)(lds + PG8_SA(b, h) + aoff + m * 2048 + k * 1024); } while (0)
; #define PG8_LDB(dst, b, h) do { _Pragma("unroll") for (int n = 0; n < 2; ++n) _Pragma("unroll") for (int k = 0; k < 2; ++k) dst[n][k] = *(const LAS bf16x8*)(lds + PG8_SB(b, h) + boff + n * 2048 + k * 1024); } while (0)
; #define PG8_MMA(ai, bj, At, Bt) do { __builtin_amdgcn_s_setprio(1); _Pragma("unroll") for (int m = 0; m < 4; ++m) _Pragma("unroll") for (int n = 0; n < 2; ++n) _Pragma("unroll") for (int k = 0; k < 2; ++k) \
;         acc[ai][bj][m][n] = __builtin_amdgcn_mfma_f32_16x16x32_bf16(Bt[n][k], At[m][k], acc[ai][bj][m][n], 0, 0, 0); __builtin_amdgcn_s_setprio(0); } while (0)
; #define PG8_WAIT_V(n) asm volatile("s_waitcnt vmcnt(" #n ")" ::: "memory")
; #define PG8_WAIT_L(n) asm volatile("s_waitcnt lgkmcnt(" #n ")" ::: "memory")
; #define PG8_BAR __builtin_amdgcn_s_barrier()
; #define PG8_SCHED __builtin_amdgcn_sched_barrier(0)
; template <class Epi>
; __device__ __forceinline__ void gemm_phase(LAS unsigned char* lds, const Gemm g, const StaticOrder& S, const Epi& E) {
;     ...
;             PG8_LDB(B0, 1, 0); PG8_SCHED; PG8_LDA(At, 1, 0); PG8_STAGE(PG8_SA(0, 1), a2 + hstep, voffA);
;             PG8_WAIT_L(8); PG8_BAR; PG8_WAIT_L(0); PG8_MMA(0, 0, At, B0); PG8_BAR; PG8_SCHED;
;             PG8_LDB(B1, 1, 1); PG8_STAGE(PG8_SB(1, 0), b3, voffB);
;             PG8_BAR; PG8_WAIT_L(0); PG8_MMA(0, 1, At, B1); PG8_BAR;
;             PG8_LDA(At, 1, 1); PG8_STAGE(PG8_SA(1, 0), a3, voffA);
;             PG8_BAR; PG8_WAIT_L(0); PG8_MMA(1, 0, At, B0); PG8_BAR; PG8_SCHED;
;             PG8_STAGE(PG8_SB(1, 1), b3 + hstep, voffB);
;             PG8_WAIT_V(6); PG8_BAR; PG8_MMA(1, 1, At, B1); PG8_BAR;
	v_mfma_f32_16x16x32_bf16 v[54:57], v[178:181], v[146:149], v[54:57]
	v_mfma_f32_16x16x32_bf16 v[50:53], v[186:189], v[146:149], v[50:53]
	v_mfma_f32_16x16x32_bf16 v[38:41], v[178:181], v[154:157], v[38:41]
	v_mfma_f32_16x16x32_bf16 v[34:37], v[186:189], v[154:157], v[34:37]
	v_mfma_f32_16x16x32_bf16 v[22:25], v[178:181], v[162:165], v[22:25]
	v_mfma_f32_16x16x32_bf16 v[18:21], v[186:189], v[162:165], v[18:21]
	v_mfma_f32_16x16x32_bf16 v[6:9], v[178:181], v[170:173], v[6:9]
	v_mfma_f32_16x16x32_bf16 v[2:5], v[186:189], v[170:173], v[2:5]
	v_mfma_f32_16x16x32_bf16 v[54:57], v[182:185], v[150:153], v[54:57]
	v_mfma_f32_16x16x32_bf16 v[50:53], v[190:193], v[150:153], v[50:53]
	v_mfma_f32_16x16x32_bf16 v[38:41], v[182:185], v[158:161], v[38:41]
	v_mfma_f32_16x16x32_bf16 v[34:37], v[190:193], v[158:161], v[34:37]
	v_mfma_f32_16x16x32_bf16 v[22:25], v[182:185], v[166:169], v[22:25]
	v_mfma_f32_16x16x32_bf16 v[18:21], v[190:193], v[166:169], v[18:21]
	v_mfma_f32_16x16x32_bf16 v[6:9], v[182:185], v[174:177], v[6:9]
	v_mfma_f32_16x16x32_bf16 v[2:5], v[190:193], v[174:177], v[2:5]
	s_barrier
	s_add_u32 s62, s62, s50
	s_addc_u32 s63, s63, 0
	s_mov_b32 m0, s72
	ds_read_b128 v[146:149], v243 offset:32768
	ds_read_b128 v[150:153], v243 offset:33792
	ds_read_b128 v[154:157], v243 offset:34816
	ds_read_b128 v[158:161], v243 offset:35840
	ds_read_b128 v[162:165], v243 offset:36864
	ds_read_b128 v[166:169], v243 offset:37888
	ds_read_b128 v[170:173], v243 offset:38912
	s_add_i32 s64, 0, 0x18000
	ds_read_b128 v[174:177], v243 offset:39936
	global_load_lds_dwordx4 v212, s[62:63]
	s_mov_b32 m0, s73
	s_nop 0
	global_load_lds_dwordx4 v210, s[62:63]
	s_waitcnt lgkmcnt(8)
	s_barrier
	s_waitcnt lgkmcnt(0)
	v_mfma_f32_16x16x32_bf16 v[142:145], v[58:61], v[146:149], v[142:145]
	v_mfma_f32_16x16x32_bf16 v[138:141], v[66:69], v[146:149], v[138:141]
	v_mfma_f32_16x16x32_bf16 v[126:129], v[58:61], v[154:157], v[126:129]
	v_mfma_f32_16x16x32_bf16 v[122:125], v[66:69], v[154:157], v[122:125]
	v_mfma_f32_16x16x32_bf16 v[110:113], v[58:61], v[162:165], v[110:113]
	v_mfma_f32_16x16x32_bf16 v[106:109], v[66:69], v[162:165], v[106:109]
	v_mfma_f32_16x16x32_bf16 v[94:97], v[58:61], v[170:173], v[94:97]
	v_mfma_f32_16x16x32_bf16 v[90:93], v[66:69], v[170:173], v[90:93]
	v_mfma_f32_16x16x32_bf16 v[142:145], v[62:65], v[150:153], v[142:145]
	v_mfma_f32_16x16x32_bf16 v[138:141], v[70:73], v[150:153], v[138:141]
	v_mfma_f32_16x16x32_bf16 v[126:129], v[62:65], v[158:161], v[126:129]
	v_mfma_f32_16x16x32_bf16 v[122:125], v[70:73], v[158:161], v[122:125]
	v_mfma_f32_16x16x32_bf16 v[110:113], v[62:65], v[166:169], v[110:113]
	v_mfma_f32_16x16x32_bf16 v[106:109], v[70:73], v[166:169], v[106:109]
	v_mfma_f32_16x16x32_bf16 v[94:97], v[62:65], v[174:177], v[94:97]
	v_mfma_f32_16x16x32_bf16 v[90:93], v[70:73], v[174:177], v[90:93]
	s_barrier
	s_add_i32 s62, 0, 0x1c000
	s_add_i32 s63, s64, s69
	s_mov_b32 m0, s63
	ds_read_b128 v[178:181], v194 offset:49152
	ds_read_b128 v[182:185], v194 offset:50176
	ds_read_b128 v[186:189], v194 offset:51200
	ds_read_b128 v[190:193], v194 offset:52224
	global_load_lds_dwordx4 v0, s[98:99]
	s_add_i32 m0, s63, 0x2000
	s_nop 0
	global_load_lds_dwordx4 v208, s[98:99]
	s_barrier
	s_waitcnt lgkmcnt(0)
	v_mfma_f32_16x16x32_bf16 v[134:137], v[178:181], v[146:149], v[134:137]
	v_mfma_f32_16x16x32_bf16 v[130:133], v[186:189], v[146:149], v[130:133]
	v_mfma_f32_16x16x32_bf16 v[118:121], v[178:181], v[154:157], v[118:121]
	v_mfma_f32_16x16x32_bf16 v[114:117], v[186:189], v[154:157], v[114:117]
	v_mfma_f32_16x16x32_bf16 v[102:105], v[178:181], v[162:165], v[102:105]
	v_mfma_f32_16x16x32_bf16 v[98:101], v[186:189], v[162:165], v[98:101]
	v_mfma_f32_16x16x32_bf16 v[86:89], v[178:181], v[170:173], v[86:89]
	v_mfma_f32_16x16x32_bf16 v[82:85], v[186:189], v[170:173], v[82:85]
	v_mfma_f32_16x16x32_bf16 v[134:137], v[182:185], v[150:153], v[134:137]
	v_mfma_f32_16x16x32_bf16 v[130:133], v[190:193], v[150:153], v[130:133]
	v_mfma_f32_16x16x32_bf16 v[118:121], v[182:185], v[158:161], v[118:121]
	v_mfma_f32_16x16x32_bf16 v[114:117], v[190:193], v[158:161], v[114:117]
	v_mfma_f32_16x16x32_bf16 v[102:105], v[182:185], v[166:169], v[102:105]
	v_mfma_f32_16x16x32_bf16 v[98:101], v[190:193], v[166:169], v[98:101]
	v_mfma_f32_16x16x32_bf16 v[86:89], v[182:185], v[174:177], v[86:89]
	v_mfma_f32_16x16x32_bf16 v[82:85], v[190:193], v[174:177], v[82:85]
	s_barrier
	ds_read_b128 v[146:149], v243 offset:49152
	ds_read_b128 v[150:153], v243 offset:50176
	ds_read_b128 v[154:157], v243 offset:51200
	ds_read_b128 v[158:161], v243 offset:52224
	ds_read_b128 v[162:165], v243 offset:53248
	ds_read_b128 v[166:169], v243 offset:54272
	ds_read_b128 v[170:173], v243 offset:55296
	s_mov_b32 m0, s75
	ds_read_b128 v[174:177], v243 offset:56320
	global_load_lds_dwordx4 v212, s[100:101]
	s_mov_b32 m0, s76
	s_nop 0
	global_load_lds_dwordx4 v210, s[100:101]
	s_waitcnt vmcnt(10)
	s_barrier
	s_waitcnt lgkmcnt(0)
	v_mfma_f32_16x16x32_bf16 v[78:81], v[58:61], v[146:149], v[78:81]
	v_mfma_f32_16x16x32_bf16 v[74:77], v[66:69], v[146:149], v[74:77]
	v_mfma_f32_16x16x32_bf16 v[46:49], v[58:61], v[154:157], v[46:49]
	v_mfma_f32_16x16x32_bf16 v[42:45], v[66:69], v[154:157], v[42:45]
	v_mfma_f32_16x16x32_bf16 v[30:33], v[58:61], v[162:165], v[30:33]
	v_mfma_f32_16x16x32_bf16 v[26:29], v[66:69], v[162:165], v[26:29]
	v_mfma_f32_16x16x32_bf16 v[14:17], v[58:61], v[170:173], v[14:17]
	v_mfma_f32_16x16x32_bf16 v[10:13], v[66:69], v[170:173], v[10:13]
	v_mfma_f32_16x16x32_bf16 v[78:81], v[62:65], v[150:153], v[78:81]
	v_mfma_f32_16x16x32_bf16 v[74:77], v[70:73], v[150:153], v[74:77]
	v_mfma_f32_16x16x32_bf16 v[46:49], v[62:65], v[158:161], v[46:49]
	v_mfma_f32_16x16x32_bf16 v[42:45], v[70:73], v[158:161], v[42:45]
	v_mfma_f32_16x16x32_bf16 v[30:33], v[62:65], v[166:169], v[30:33]
	v_mfma_f32_16x16x32_bf16 v[26:29], v[70:73], v[166:169], v[26:29]
	v_mfma_f32_16x16x32_bf16 v[14:17], v[62:65], v[174:177], v[14:17]
	v_mfma_f32_16x16x32_bf16 v[10:13], v[70:73], v[174:177], v[10:13]
	s_barrier
; #define PG8_WAIT_V(n) asm volatile("s_waitcnt vmcnt(" #n ")" ::: "memory")
;     __device__ __forceinline__ void operator()(const AccT& acc, const Unit& u, int wr, int wc, int fr, int fq) const {
;         const int row0 = u.pm * BM + wr * 64 + fr, col0 = u.pn * BM + wc * 32 + 8 * fq;
;         f32x4 gv[2][2];
; #pragma unroll
;         for (int bj = 0; bj < 2; ++bj)
; #pragma unroll
;             for (int n = 0; n < 2; ++n) gv[bj][n] = *(const f32x4*)(g + col0 + bj * HALF + 4 * n);
; #pragma unroll
;         for (int ai = 0; ai < 2; ++ai) {
;             f32x4 xv[4][2][2];
; #pragma unroll
;             for (int m = 0; m < 4; ++m)
; #pragma unroll
;                 for (int bj = 0; bj < 2; ++bj) {
;                     const size_t p = (size_t)(row0 + ai * HALF + m * 16) * DM + col0 + bj * HALF;
;                     xv[m][bj][0] = __builtin_nontemporal_load((const f32x4*)(xin + p)); xv[m][bj][1] = __builtin_nontemporal_load((const f32x4*)(xin + p + 4));
;                 }
; #pragma unroll
;             for (int m = 0; m < 4; ++m) {
;                 const int row = row0 + ai * HALF + m * 16;
;                 float ssa = 0.f;
; #pragma unroll
;                 for (int bj = 0; bj < 2; ++bj) {
;                     const size_t p = (size_t)row * DM + col0 + bj * HALF;
;                     const f32x4 x0 = xv[m][bj][0] + acc[ai][bj][m][0] * alpha, x1 = xv[m][bj][1] + acc[ai][bj][m][1] * alpha;
;                     __builtin_nontemporal_store(x0, (f32x4*)(xout + p)); __builtin_nontemporal_store(x1, (f32x4*)(xout + p + 4));
;                     ssa += (x0[0] * x0[0] + x0[1] * x0[1]) + (x0[2] * x0[2] + x0[3] * x0[3]) + (x1[0] * x1[0] + x1[1] * x1[1]) + (x1[2] * x1[2] + x1[3] * x1[3]);
;                     const f32x4 h0 = x0 * gv[bj][0], h1 = x1 * gv[bj][1];
;                     u32x4 w; w.x = pk2(h0[0], h0[1]); w.y = pk2(h0[2], h0[3]); w.z = pk2(h1[0], h1[1]); w.w = pk2(h1[2], h1[3]);
;                     *(u32x4*)(h + p) = w;
;                 }
;                 ssa += __shfl_xor(ssa, 16); ssa += __shfl_xor(ssa, 32);
;                 if (fq == 0) unsafeAtomicAdd(ssout + row, ssa);
; template <class Epi>
; __device__ __forceinline__ void gemm_phase(LAS unsigned char* lds, const Gemm g, const StaticOrder& S, const Epi& E) {
;     ...
;             PG8_WAIT_V(6); PG8_BAR; PG8_MMA(1, 1, At, B1); PG8_BAR;
;         }
;         E(acc, cur, wr, wc, fr, fq);
	ds_read_b128 v[58:61], v194
	ds_read_b128 v[62:65], v194 offset:1024
	ds_read_b128 v[66:69], v194 offset:2048
	s_add_u32 s60, s60, 0x100
	s_addc_u32 s61, s61, 0
	s_add_u32 s82, s82, 0x100
	s_addc_u32 s83, s83, 0
	ds_read_b128 v[70:73], v194 offset:3072
	s_add_i32 s62, s62, s69
	s_mov_b32 m0, s62
	s_nop 0
	global_load_lds_dwordx4 v0, vcc
	s_add_i32 m0, s62, 0x2000
	s_nop 0
	global_load_lds_dwordx4 v208, vcc
	s_waitcnt vmcnt(6)
	s_barrier
	v_mfma_f32_16x16x32_bf16 v[54:57], v[178:181], v[146:149], v[54:57]
	v_mfma_f32_16x16x32_bf16 v[50:53], v[186:189], v[146:149], v[50:53]
	v_mfma_f32_16x16x32_bf16 v[38:41], v[178:181], v[154:157], v[38:41]
	v_mfma_f32_16x16x32_bf16 v[34:37], v[186:189], v[154:157], v[34:37]
	v_mfma_f32_16x16x32_bf16 v[22:25], v[178:181], v[162:165], v[22:25]
	v_mfma_f32_16x16x32_bf16 v[18:21], v[186:189], v[162:165], v[18:21]
	v_mfma_f32_16x16x32_bf16 v[6:9], v[178:181], v[170:173], v[6:9]
	v_mfma_f32_16x16x32_bf16 v[2:5], v[186:189], v[170:173], v[2:5]
	v_mfma_f32_16x16x32_bf16 v[54:57], v[182:185], v[150:153], v[54:57]
	v_mfma_f32_16x16x32_bf16 v[50:53], v[190:193], v[150:153], v[50:53]
	v_mfma_f32_16x16x32_bf16 v[38:41], v[182:185], v[158:161], v[38:41]
	v_mfma_f32_16x16x32_bf16 v[34:37], v[190:193], v[158:161], v[34:37]
	v_mfma_f32_16x16x32_bf16 v[22:25], v[182:185], v[166:169], v[22:25]
	v_mfma_f32_16x16x32_bf16 v[18:21], v[190:193], v[166:169], v[18:21]
	v_mfma_f32_16x16x32_bf16 v[6:9], v[182:185], v[174:177], v[6:9]
	v_mfma_f32_16x16x32_bf16 v[2:5], v[190:193], v[174:177], v[2:5]
	s_cmp_ge_u32 s84, s74
	s_mov_b32 s62, s84
	s_barrier
	s_cbranch_scc0 .LBB0_654
	s_waitcnt lgkmcnt(0)
	v_lshl_or_b32 v218, s81, 8, v242
	v_ashrrev_i32_e32 v219, 31, v218
	v_lshl_add_u32 v220, s80, 8, v240
	v_lshlrev_b64 v[146:147], 2, v[218:219]
	v_ashrrev_i32_e32 v221, 31, v220
	v_lshl_add_u64 v[62:63], s[44:45], 0, v[146:147]
	v_lshl_add_u64 v[222:223], s[54:55], 0, v[146:147]
	v_lshlrev_b64 v[146:147], 13, v[220:221]
	v_lshl_add_u64 v[146:147], v[222:223], 0, v[146:147]
	global_load_dwordx4 v[66:69], v[62:63], off offset:16
	global_load_dwordx4 v[70:73], v[62:63], off
	global_load_dwordx4 v[58:61], v[62:63], off offset:528
	s_nop 0
	global_load_dwordx4 v[62:65], v[62:63], off offset:512
	s_nop 0
	global_load_dwordx4 v[246:249], v[146:147], off offset:16 nt
	global_load_dwordx4 v[202:205], v[146:147], off nt
	global_load_dwordx4 v[194:197], v[146:147], off offset:528 nt
	global_load_dwordx4 v[198:201], v[146:147], off offset:512 nt
	v_or_b32_e32 v228, 16, v220
	v_and_b32_e32 v149, 64, v234
	v_ashrrev_i32_e32 v229, 31, v228
	v_xor_b32_e32 v148, 16, v234
	v_add_u32_e32 v149, 64, v149
	v_lshlrev_b64 v[146:147], 13, v[228:229]
	v_or_b32_e32 v226, 32, v220
	v_cmp_lt_i32_e32 vcc, v148, v149
	v_lshl_add_u64 v[146:147], v[222:223], 0, v[146:147]
	v_ashrrev_i32_e32 v227, 31, v226
	v_cndmask_b32_e32 v148, v234, v148, vcc
	global_load_dwordx4 v[186:189], v[146:147], off offset:16 nt
	global_load_dwordx4 v[190:193], v[146:147], off nt
	global_load_dwordx4 v[178:181], v[146:147], off offset:528 nt
	global_load_dwordx4 v[182:185], v[146:147], off offset:512 nt
	v_lshlrev_b64 v[146:147], 13, v[226:227]
	v_or_b32_e32 v224, 48, v220
	v_lshlrev_b32_e32 v245, 2, v148
	v_xor_b32_e32 v148, 32, v234
	v_lshl_add_u64 v[146:147], v[222:223], 0, v[146:147]
	v_ashrrev_i32_e32 v225, 31, v224
	v_cmp_lt_i32_e32 vcc, v148, v149
	global_load_dwordx4 v[170:173], v[146:147], off offset:16 nt
	global_load_dwordx4 v[174:177], v[146:147], off nt
	global_load_dwordx4 v[154:157], v[146:147], off offset:528 nt
	global_load_dwordx4 v[158:161], v[146:147], off offset:512 nt
	v_lshlrev_b64 v[146:147], 13, v[224:225]
	v_cndmask_b32_e32 v148, v234, v148, vcc
	v_lshl_add_u64 v[150:151], v[222:223], 0, v[146:147]
	v_lshlrev_b32_e32 v244, 2, v148
	global_load_dwordx4 v[162:165], v[150:151], off offset:16 nt
	global_load_dwordx4 v[166:169], v[150:151], off nt
	global_load_dwordx4 v[146:149], v[150:151], off offset:528 nt
	s_nop 0
	global_load_dwordx4 v[150:153], v[150:151], off offset:512 nt
	v_lshlrev_b64 v[230:231], 11, v[220:221]
	v_readlane_b32 s60, v251, 56
	v_lshl_add_u64 v[230:231], v[230:231], 0, v[218:219]
	v_readlane_b32 s61, v251, 57
	v_readlane_b32 s62, v254, 8
	v_readlane_b32 s63, v254, 9
	s_waitcnt vmcnt(0)
	v_pk_fma_f32 v[140:141], s[58:59], v[140:141], v[248:249]
	v_pk_fma_f32 v[144:145], s[58:59], v[144:145], v[204:205]
	v_pk_fma_f32 v[142:143], s[46:47], v[142:143], v[202:203]
	v_lshl_add_u64 v[202:203], v[230:231], 2, s[60:61]
	v_pk_fma_f32 v[138:139], s[46:47], v[138:139], v[246:247]
	global_store_dwordx4 v[202:203], v[142:145], off nt
	global_store_dwordx4 v[202:203], v[138:141], off offset:16 nt
	v_mul_f32_e32 v202, v143, v143
	v_mul_f32_e32 v203, v145, v145
	v_fmac_f32_e32 v202, v142, v142
	v_fmac_f32_e32 v203, v144, v144
	v_add_f32_e32 v202, v202, v203
	v_mul_f32_e32 v203, v139, v139
	v_fmac_f32_e32 v203, v138, v138
	v_add_f32_e32 v202, v203, v202
	v_mul_f32_e32 v203, v141, v141
	v_fmac_f32_e32 v203, v140, v140
	v_add_f32_e32 v204, v203, v202
	v_pk_mul_f32 v[144:145], v[72:73], v[144:145]
	v_pk_mul_f32 v[142:143], v[70:71], v[142:143]
	v_pk_mul_f32 v[202:203], v[68:69], v[140:141]
	v_pk_mul_f32 v[140:141], v[66:67], v[138:139]
	v_cvt_pk_bf16_f32 v138, v142, v143
	v_cvt_pk_bf16_f32 v139, v144, v145
	v_cvt_pk_bf16_f32 v140, v140, v141
	v_cvt_pk_bf16_f32 v141, v202, v203
	v_lshl_add_u64 v[142:143], v[230:231], 1, s[62:63]
	v_or_b32_e32 v230, 0x80, v230
	global_store_dwordx4 v[142:143], v[138:141], off
	v_pk_fma_f32 v[136:137], s[58:59], v[136:137], v[200:201]
	v_pk_fma_f32 v[134:135], s[46:47], v[134:135], v[198:199]
	v_lshl_add_u64 v[138:139], v[230:231], 2, s[60:61]
	v_pk_fma_f32 v[132:133], s[58:59], v[132:133], v[196:197]
	v_pk_fma_f32 v[130:131], s[46:47], v[130:131], v[194:195]
	global_store_dwordx4 v[138:139], v[134:137], off nt
	global_store_dwordx4 v[138:139], v[130:133], off offset:16 nt
	v_mul_f32_e32 v138, v135, v135
	v_mul_f32_e32 v139, v137, v137
	v_fmac_f32_e32 v138, v134, v134
	v_fmac_f32_e32 v139, v136, v136
	v_add_f32_e32 v138, v138, v139
	v_mul_f32_e32 v139, v131, v131
	v_fmac_f32_e32 v139, v130, v130
	v_add_f32_e32 v138, v139, v138
	v_mul_f32_e32 v139, v133, v133
	v_fmac_f32_e32 v139, v132, v132
	v_add_f32_e32 v138, v139, v138
	v_add_f32_e32 v140, v204, v138
	v_pk_mul_f32 v[136:137], v[64:65], v[136:137]
	v_pk_mul_f32 v[134:135], v[62:63], v[134:135]
	v_pk_mul_f32 v[138:139], v[60:61], v[132:133]
	v_pk_mul_f32 v[132:133], v[58:59], v[130:131]
	v_cvt_pk_bf16_f32 v130, v134, v135
	v_cvt_pk_bf16_f32 v131, v136, v137
	v_cvt_pk_bf16_f32 v132, v132, v133
	v_cvt_pk_bf16_f32 v133, v138, v139
	v_lshl_add_u64 v[134:135], v[230:231], 1, s[62:63]
	global_store_dwordx4 v[134:135], v[130:133], off
	ds_bpermute_b32 v130, v245, v140
	v_lshl_add_u64 v[138:139], v[220:221], 2, s[56:57]
	s_waitcnt lgkmcnt(0)
	v_add_f32_e32 v130, v140, v130
	ds_bpermute_b32 v131, v244, v130
	s_and_saveexec_b64 s[60:61], s[36:37]
	s_cbranch_execz .LBB0_657
	s_waitcnt lgkmcnt(0)
	v_add_f32_e32 v130, v130, v131
	global_atomic_add_f32 v[138:139], v130, off
